# chain-ordered MFMA pairs + first K-loop iteration peeled with C=0 MFMAs instead of 128-register accumulator zero-init (6 GEMM instances)
# speedup vs baseline: 1.0039x; 1.0027x over previous
.LBB0_368:
	s_ashr_i32 s55, s54, 31
	s_lshl_b64 s[2:3], s[54:55], 20
	s_add_u32 s58, s64, s2
	s_addc_u32 s59, s65, s3
	s_and_b64 s[2:3], s[38:39], exec
	s_cselect_b32 s40, s59, s19
	s_cselect_b32 s41, s58, s18
	s_ashr_i32 s57, s56, 31
	s_lshl_b64 s[2:3], s[56:57], 20
	s_add_u32 s60, s66, s2
	s_addc_u32 s61, s67, s3
	s_and_b64 s[2:3], s[38:39], exec
	s_mul_hi_i32 s5, s62, 0x78787879
	s_cselect_b32 s57, s61, s27
	s_cselect_b32 s4, s60, s26
	s_lshr_b32 s15, s5, 31
	s_ashr_i32 s5, s5, 3
	s_add_i32 s5, s5, s15
	s_mul_i32 s15, s5, 17
	s_mul_i32 s23, s5, 0xf400
	s_mul_hi_i32 s28, s5, 0xf400
	s_mul_hi_i32 s5, s14, 0x55555556
	s_sub_i32 s22, s62, s15
	s_lshr_b32 s15, s5, 31
	s_lshl_b32 s74, s62, 8
	s_add_i32 s20, s5, s15
	s_ashr_i32 s75, s74, 31
	s_lshl_b32 s24, s14, 8
	s_mul_i32 s5, s20, -3
	s_lshl_b64 s[2:3], s[74:75], 5
	s_ashr_i32 s25, s24, 31
	s_add_i32 s55, s5, s14
	s_cmp_lg_u32 s55, 0
	s_cselect_b64 s[14:15], -1, 0
	s_and_b64 s[16:17], s[44:45], s[14:15]
	s_lshl_b32 s14, s20, 8
	s_lshl_b32 s20, s55, 7
	s_addk_i32 s20, 0xff80
	s_ashr_i32 s15, s14, 31
	s_ashr_i32 s21, s20, 31
	s_cmp_lg_u32 s22, 0
	s_cselect_b32 s29, s28, 0
	s_cselect_b32 s28, s23, 0x7a000
	s_lshl_b64 s[22:23], s[14:15], 2
	s_add_u32 s15, s79, s22
	s_addc_u32 s22, s80, s23
	s_lshl_b64 s[20:21], s[20:21], 2
	s_add_u32 s20, s15, s20
	s_addc_u32 s21, s22, s21
	s_add_u32 s22, s81, s2
	s_addc_u32 s23, s82, s3
	s_lshl_b64 s[2:3], s[28:29], 2
	s_add_u32 s15, s83, s2
	s_addc_u32 s28, s84, s3
	s_lshl_b64 s[2:3], s[24:25], 2
	s_add_u32 s24, s15, s2
	s_addc_u32 s25, s28, s3
	s_add_u32 s15, s26, 0x100
	s_mov_b32 s5, 0
	s_addc_u32 s75, s27, 0
	s_add_u32 s26, s18, 0x100
	s_addc_u32 s27, s19, 0
	s_cmp_eq_u32 s5, 30
	s_cselect_b32 s31, s40, s27
	s_cselect_b32 s30, s41, s26
	s_cselect_b32 s29, s57, s75
	s_cselect_b32 s28, s4, s15
	s_add_i32 s2, 0, 0x10000
	v_add_u32_e32 v152, s2, v154
	s_add_i32 vcc_lo, 0, 0x14000
	ds_read_b128 v[140:143], v152
	ds_read_b128 v[144:147], v152 offset:1024
	ds_read_b128 v[148:151], v152 offset:2048
	ds_read_b128 v[156:159], v152 offset:3072
	v_add_u32_e32 v152, vcc_lo, v154
	ds_read_b128 v[160:163], v152
	ds_read_b128 v[164:167], v152 offset:1024
	ds_read_b128 v[168:171], v152 offset:2048
	ds_read_b128 v[172:175], v152 offset:3072
	v_lshl_add_u64 v[152:153], s[18:19], 0, v[136:137]
	s_add_i32 m0, s63, 0xc000
	ds_read_b128 v[176:179], v155
	ds_read_b128 v[180:183], v155 offset:1024
	ds_read_b128 v[184:187], v155 offset:2048
	ds_read_b128 v[188:191], v155 offset:3072
	ds_read_b128 v[192:195], v155 offset:4096
	ds_read_b128 v[196:199], v155 offset:5120
	ds_read_b128 v[200:203], v155 offset:6144
	ds_read_b128 v[204:207], v155 offset:7168
	global_load_lds_dwordx4 v[152:153], off
	v_lshl_add_u64 v[152:153], s[18:19], 0, v[138:139]
	s_add_i32 m0, s63, 0xe000
	s_nop 0
	global_load_lds_dwordx4 v[152:153], off
	s_waitcnt vmcnt(8)
	s_waitcnt lgkmcnt(0)
	s_barrier
	s_setprio 1
	s_waitcnt lgkmcnt(0)
	v_mfma_f32_16x16x32_bf16 v[96:99], v[140:143], v[176:179], 0
	v_mfma_f32_16x16x32_bf16 v[96:99], v[144:147], v[180:183], v[96:99]
	v_mfma_f32_16x16x32_bf16 v[124:127], v[140:143], v[184:187], 0
	v_mfma_f32_16x16x32_bf16 v[124:127], v[144:147], v[188:191], v[124:127]
	v_mfma_f32_16x16x32_bf16 v[120:123], v[140:143], v[192:195], 0
	v_mfma_f32_16x16x32_bf16 v[120:123], v[144:147], v[196:199], v[120:123]
	v_mfma_f32_16x16x32_bf16 v[84:87], v[140:143], v[200:203], 0
	v_mfma_f32_16x16x32_bf16 v[84:87], v[144:147], v[204:207], v[84:87]
	v_mfma_f32_16x16x32_bf16 v[56:59], v[148:151], v[176:179], 0
	v_mfma_f32_16x16x32_bf16 v[56:59], v[156:159], v[180:183], v[56:59]
	v_mfma_f32_16x16x32_bf16 v[116:119], v[148:151], v[184:187], 0
	v_mfma_f32_16x16x32_bf16 v[116:119], v[156:159], v[188:191], v[116:119]
	v_mfma_f32_16x16x32_bf16 v[112:115], v[148:151], v[192:195], 0
	v_mfma_f32_16x16x32_bf16 v[112:115], v[156:159], v[196:199], v[112:115]
	v_mfma_f32_16x16x32_bf16 v[48:51], v[148:151], v[200:203], 0
	v_mfma_f32_16x16x32_bf16 v[48:51], v[156:159], v[204:207], v[48:51]
	s_setprio 0
	s_setprio 1
	v_mfma_f32_16x16x32_bf16 v[100:103], v[160:163], v[176:179], 0
	v_mfma_f32_16x16x32_bf16 v[100:103], v[164:167], v[180:183], v[100:103]
	v_mfma_f32_16x16x32_bf16 v[88:91], v[160:163], v[184:187], 0
	v_mfma_f32_16x16x32_bf16 v[88:91], v[164:167], v[188:191], v[88:91]
	v_mfma_f32_16x16x32_bf16 v[72:75], v[160:163], v[192:195], 0
	v_mfma_f32_16x16x32_bf16 v[72:75], v[164:167], v[196:199], v[72:75]
	v_mfma_f32_16x16x32_bf16 v[64:67], v[160:163], v[200:203], 0
	v_mfma_f32_16x16x32_bf16 v[64:67], v[164:167], v[204:207], v[64:67]
	v_mfma_f32_16x16x32_bf16 v[60:63], v[168:171], v[176:179], 0
	v_mfma_f32_16x16x32_bf16 v[60:63], v[172:175], v[180:183], v[60:63]
	v_mfma_f32_16x16x32_bf16 v[44:47], v[168:171], v[184:187], 0
	v_mfma_f32_16x16x32_bf16 v[44:47], v[172:175], v[188:191], v[44:47]
	v_mfma_f32_16x16x32_bf16 v[32:35], v[168:171], v[192:195], 0
	v_mfma_f32_16x16x32_bf16 v[32:35], v[172:175], v[196:199], v[32:35]
	v_mfma_f32_16x16x32_bf16 v[24:27], v[168:171], v[200:203], 0
	v_mfma_f32_16x16x32_bf16 v[24:27], v[172:175], v[204:207], v[24:27]
	s_setprio 0
	s_barrier
	s_nop 1
	s_add_i32 s2, s2, s69
	v_lshl_add_u64 v[152:153], s[28:29], 0, v[130:131]
	s_mov_b32 m0, s2
	ds_read_b128 v[176:179], v155 offset:16384
	ds_read_b128 v[180:183], v155 offset:17408
	ds_read_b128 v[184:187], v155 offset:18432
	ds_read_b128 v[188:191], v155 offset:19456
	ds_read_b128 v[192:195], v155 offset:20480
	ds_read_b128 v[196:199], v155 offset:21504
	ds_read_b128 v[200:203], v155 offset:22528
	ds_read_b128 v[204:207], v155 offset:23552
	global_load_lds_dwordx4 v[152:153], off
	s_add_i32 m0, s2, 0x2000
	s_add_u32 s2, s28, 0x80000
	v_lshl_add_u64 v[208:209], s[28:29], 0, v[134:135]
	s_addc_u32 s3, s29, 0
	s_add_i32 s18, vcc_lo, s69
	global_load_lds_dwordx4 v[208:209], off
	v_lshl_add_u64 v[210:211], s[2:3], 0, v[130:131]
	s_mov_b32 m0, s18
	v_lshl_add_u64 v[214:215], s[30:31], 0, v[132:133]
	global_load_lds_dwordx4 v[210:211], off
	v_lshl_add_u64 v[210:211], s[2:3], 0, v[134:135]
	s_add_i32 m0, s18, 0x2000
	s_nop 0
	global_load_lds_dwordx4 v[210:211], off
	v_lshl_add_u64 v[210:211], s[30:31], 0, v[128:129]
	s_mov_b32 m0, s63
	s_nop 0
	global_load_lds_dwordx4 v[210:211], off
	s_mov_b32 m0, s70
	s_nop 0
	global_load_lds_dwordx4 v[214:215], off
	s_waitcnt vmcnt(8)
	s_waitcnt lgkmcnt(0)
	s_barrier
	s_setprio 1
	s_waitcnt lgkmcnt(0)
	v_mfma_f32_16x16x32_bf16 v[92:95], v[140:143], v[176:179], 0
	v_mfma_f32_16x16x32_bf16 v[92:95], v[144:147], v[180:183], v[92:95]
	v_mfma_f32_16x16x32_bf16 v[108:111], v[140:143], v[184:187], 0
	v_mfma_f32_16x16x32_bf16 v[108:111], v[144:147], v[188:191], v[108:111]
	v_mfma_f32_16x16x32_bf16 v[104:107], v[140:143], v[192:195], 0
	v_mfma_f32_16x16x32_bf16 v[104:107], v[144:147], v[196:199], v[104:107]
	v_mfma_f32_16x16x32_bf16 v[76:79], v[140:143], v[200:203], 0
	v_mfma_f32_16x16x32_bf16 v[76:79], v[144:147], v[204:207], v[76:79]
	v_mfma_f32_16x16x32_bf16 v[52:55], v[148:151], v[176:179], 0
	v_mfma_f32_16x16x32_bf16 v[52:55], v[156:159], v[180:183], v[52:55]
	v_mfma_f32_16x16x32_bf16 v[80:83], v[148:151], v[184:187], 0
	v_mfma_f32_16x16x32_bf16 v[80:83], v[156:159], v[188:191], v[80:83]
	v_mfma_f32_16x16x32_bf16 v[68:71], v[148:151], v[192:195], 0
	v_mfma_f32_16x16x32_bf16 v[68:71], v[156:159], v[196:199], v[68:71]
	v_mfma_f32_16x16x32_bf16 v[36:39], v[148:151], v[200:203], 0
	v_mfma_f32_16x16x32_bf16 v[36:39], v[156:159], v[204:207], v[36:39]
	s_setprio 0
	s_setprio 1
	v_mfma_f32_16x16x32_bf16 v[40:43], v[160:163], v[176:179], 0
	v_mfma_f32_16x16x32_bf16 v[40:43], v[164:167], v[180:183], v[40:43]
	v_mfma_f32_16x16x32_bf16 v[28:31], v[160:163], v[184:187], 0
	v_mfma_f32_16x16x32_bf16 v[28:31], v[164:167], v[188:191], v[28:31]
	v_mfma_f32_16x16x32_bf16 v[20:23], v[160:163], v[192:195], 0
	v_mfma_f32_16x16x32_bf16 v[20:23], v[164:167], v[196:199], v[20:23]
	v_mfma_f32_16x16x32_bf16 v[16:19], v[160:163], v[200:203], 0
	v_mfma_f32_16x16x32_bf16 v[16:19], v[164:167], v[204:207], v[16:19]
	v_mfma_f32_16x16x32_bf16 v[12:15], v[168:171], v[176:179], 0
	v_mfma_f32_16x16x32_bf16 v[12:15], v[172:175], v[180:183], v[12:15]
	v_mfma_f32_16x16x32_bf16 v[8:11], v[168:171], v[184:187], 0
	v_mfma_f32_16x16x32_bf16 v[8:11], v[172:175], v[188:191], v[8:11]
	v_mfma_f32_16x16x32_bf16 v[4:7], v[168:171], v[192:195], 0
	v_mfma_f32_16x16x32_bf16 v[4:7], v[172:175], v[196:199], v[4:7]
	v_mfma_f32_16x16x32_bf16 v[0:3], v[168:171], v[200:203], 0
	v_mfma_f32_16x16x32_bf16 v[0:3], v[172:175], v[204:207], v[0:3]
	s_setprio 0
	s_barrier
	s_nop 1
	s_add_i32 s18, 0, 0x18000
	s_add_i32 s19, 0, 0x1c000
	v_add_u32_e32 v156, s18, v154
	v_add_u32_e32 v172, s19, v154
	ds_read_b128 v[140:143], v156
	ds_read_b128 v[144:147], v156 offset:1024
	ds_read_b128 v[148:151], v156 offset:2048
	ds_read_b128 v[156:159], v156 offset:3072
	ds_read_b128 v[160:163], v172
	ds_read_b128 v[164:167], v172 offset:1024
	ds_read_b128 v[168:171], v172 offset:2048
	ds_read_b128 v[172:175], v172 offset:3072
	s_add_u32 s2, s30, 0x80000
	s_addc_u32 s3, s31, 0
	s_mov_b32 m0, s71
	v_lshl_add_u64 v[216:217], s[2:3], 0, v[128:129]
	ds_read_b128 v[176:179], v155 offset:32768
	ds_read_b128 v[180:183], v155 offset:33792
	ds_read_b128 v[184:187], v155 offset:34816
	ds_read_b128 v[188:191], v155 offset:35840
	ds_read_b128 v[192:195], v155 offset:36864
	ds_read_b128 v[196:199], v155 offset:37888
	ds_read_b128 v[200:203], v155 offset:38912
	ds_read_b128 v[204:207], v155 offset:39936
	global_load_lds_dwordx4 v[216:217], off
	v_lshl_add_u64 v[216:217], s[2:3], 0, v[132:133]
	s_mov_b32 m0, s76
	s_nop 0
	global_load_lds_dwordx4 v[216:217], off
	s_waitcnt vmcnt(8)
	s_waitcnt lgkmcnt(0)
	s_barrier
	s_setprio 1
	s_waitcnt lgkmcnt(0)
	v_mfma_f32_16x16x32_bf16 v[96:99], v[140:143], v[176:179], v[96:99]
	v_mfma_f32_16x16x32_bf16 v[96:99], v[144:147], v[180:183], v[96:99]
	v_mfma_f32_16x16x32_bf16 v[124:127], v[140:143], v[184:187], v[124:127]
	v_mfma_f32_16x16x32_bf16 v[124:127], v[144:147], v[188:191], v[124:127]
	v_mfma_f32_16x16x32_bf16 v[120:123], v[140:143], v[192:195], v[120:123]
	v_mfma_f32_16x16x32_bf16 v[120:123], v[144:147], v[196:199], v[120:123]
	v_mfma_f32_16x16x32_bf16 v[84:87], v[140:143], v[200:203], v[84:87]
	v_mfma_f32_16x16x32_bf16 v[84:87], v[144:147], v[204:207], v[84:87]
	v_mfma_f32_16x16x32_bf16 v[56:59], v[148:151], v[176:179], v[56:59]
	v_mfma_f32_16x16x32_bf16 v[56:59], v[156:159], v[180:183], v[56:59]
	v_mfma_f32_16x16x32_bf16 v[116:119], v[148:151], v[184:187], v[116:119]
	v_mfma_f32_16x16x32_bf16 v[116:119], v[156:159], v[188:191], v[116:119]
	v_mfma_f32_16x16x32_bf16 v[112:115], v[148:151], v[192:195], v[112:115]
	v_mfma_f32_16x16x32_bf16 v[112:115], v[156:159], v[196:199], v[112:115]
	v_mfma_f32_16x16x32_bf16 v[48:51], v[148:151], v[200:203], v[48:51]
	v_mfma_f32_16x16x32_bf16 v[48:51], v[156:159], v[204:207], v[48:51]
	s_setprio 0
	s_setprio 1
	v_mfma_f32_16x16x32_bf16 v[100:103], v[160:163], v[176:179], v[100:103]
	v_mfma_f32_16x16x32_bf16 v[100:103], v[164:167], v[180:183], v[100:103]
	v_mfma_f32_16x16x32_bf16 v[88:91], v[160:163], v[184:187], v[88:91]
	v_mfma_f32_16x16x32_bf16 v[88:91], v[164:167], v[188:191], v[88:91]
	v_mfma_f32_16x16x32_bf16 v[72:75], v[160:163], v[192:195], v[72:75]
	v_mfma_f32_16x16x32_bf16 v[72:75], v[164:167], v[196:199], v[72:75]
	v_mfma_f32_16x16x32_bf16 v[64:67], v[160:163], v[200:203], v[64:67]
	v_mfma_f32_16x16x32_bf16 v[64:67], v[164:167], v[204:207], v[64:67]
	v_mfma_f32_16x16x32_bf16 v[60:63], v[168:171], v[176:179], v[60:63]
	v_mfma_f32_16x16x32_bf16 v[60:63], v[172:175], v[180:183], v[60:63]
	v_mfma_f32_16x16x32_bf16 v[44:47], v[168:171], v[184:187], v[44:47]
	v_mfma_f32_16x16x32_bf16 v[44:47], v[172:175], v[188:191], v[44:47]
	v_mfma_f32_16x16x32_bf16 v[32:35], v[168:171], v[192:195], v[32:35]
	v_mfma_f32_16x16x32_bf16 v[32:35], v[172:175], v[196:199], v[32:35]
	v_mfma_f32_16x16x32_bf16 v[24:27], v[168:171], v[200:203], v[24:27]
	v_mfma_f32_16x16x32_bf16 v[24:27], v[172:175], v[204:207], v[24:27]
	s_setprio 0
	s_barrier
	s_nop 1
	s_add_i32 s2, s18, s69
	v_lshl_add_u64 v[152:153], v[152:153], 0, s[72:73]
	s_mov_b32 m0, s2
	ds_read_b128 v[176:179], v155 offset:49152
	ds_read_b128 v[180:183], v155 offset:50176
	ds_read_b128 v[184:187], v155 offset:51200
	ds_read_b128 v[188:191], v155 offset:52224
	ds_read_b128 v[192:195], v155 offset:53248
	ds_read_b128 v[196:199], v155 offset:54272
	ds_read_b128 v[200:203], v155 offset:55296
	ds_read_b128 v[204:207], v155 offset:56320
	global_load_lds_dwordx4 v[152:153], off
	s_add_i32 m0, s2, 0x2000
	s_add_u32 s2, s28, 0x80080
	v_lshl_add_u64 v[152:153], v[208:209], 0, s[72:73]
	s_addc_u32 s3, s29, 0
	s_add_i32 s18, s19, s69
	global_load_lds_dwordx4 v[152:153], off
	v_lshl_add_u64 v[152:153], s[2:3], 0, v[130:131]
	s_mov_b32 m0, s18
	s_nop 0
	global_load_lds_dwordx4 v[152:153], off
	v_lshl_add_u64 v[152:153], s[2:3], 0, v[134:135]
	s_add_i32 m0, s18, 0x2000
	s_nop 0
	global_load_lds_dwordx4 v[152:153], off
	v_lshl_add_u64 v[152:153], v[210:211], 0, s[72:73]
	s_mov_b32 m0, s87
	s_nop 0
	global_load_lds_dwordx4 v[152:153], off
	v_lshl_add_u64 v[152:153], v[214:215], 0, s[72:73]
	s_mov_b32 m0, s88
	s_nop 0
	global_load_lds_dwordx4 v[152:153], off
	s_waitcnt vmcnt(8)
	s_waitcnt lgkmcnt(0)
	s_barrier
	s_setprio 1
	s_waitcnt lgkmcnt(0)
	v_mfma_f32_16x16x32_bf16 v[92:95], v[140:143], v[176:179], v[92:95]
	v_mfma_f32_16x16x32_bf16 v[92:95], v[144:147], v[180:183], v[92:95]
	v_mfma_f32_16x16x32_bf16 v[108:111], v[140:143], v[184:187], v[108:111]
	v_mfma_f32_16x16x32_bf16 v[108:111], v[144:147], v[188:191], v[108:111]
	v_mfma_f32_16x16x32_bf16 v[104:107], v[140:143], v[192:195], v[104:107]
	v_mfma_f32_16x16x32_bf16 v[104:107], v[144:147], v[196:199], v[104:107]
	v_mfma_f32_16x16x32_bf16 v[76:79], v[140:143], v[200:203], v[76:79]
	v_mfma_f32_16x16x32_bf16 v[76:79], v[144:147], v[204:207], v[76:79]
	v_mfma_f32_16x16x32_bf16 v[52:55], v[148:151], v[176:179], v[52:55]
	v_mfma_f32_16x16x32_bf16 v[52:55], v[156:159], v[180:183], v[52:55]
	v_mfma_f32_16x16x32_bf16 v[80:83], v[148:151], v[184:187], v[80:83]
	v_mfma_f32_16x16x32_bf16 v[80:83], v[156:159], v[188:191], v[80:83]
	v_mfma_f32_16x16x32_bf16 v[68:71], v[148:151], v[192:195], v[68:71]
	v_mfma_f32_16x16x32_bf16 v[68:71], v[156:159], v[196:199], v[68:71]
	v_mfma_f32_16x16x32_bf16 v[36:39], v[148:151], v[200:203], v[36:39]
	v_mfma_f32_16x16x32_bf16 v[36:39], v[156:159], v[204:207], v[36:39]
	s_setprio 0
	s_setprio 1
	v_mfma_f32_16x16x32_bf16 v[40:43], v[160:163], v[176:179], v[40:43]
	v_mfma_f32_16x16x32_bf16 v[40:43], v[164:167], v[180:183], v[40:43]
	v_mfma_f32_16x16x32_bf16 v[28:31], v[160:163], v[184:187], v[28:31]
	v_mfma_f32_16x16x32_bf16 v[28:31], v[164:167], v[188:191], v[28:31]
	v_mfma_f32_16x16x32_bf16 v[20:23], v[160:163], v[192:195], v[20:23]
	v_mfma_f32_16x16x32_bf16 v[20:23], v[164:167], v[196:199], v[20:23]
	v_mfma_f32_16x16x32_bf16 v[16:19], v[160:163], v[200:203], v[16:19]
	v_mfma_f32_16x16x32_bf16 v[16:19], v[164:167], v[204:207], v[16:19]
	v_mfma_f32_16x16x32_bf16 v[12:15], v[168:171], v[176:179], v[12:15]
	v_mfma_f32_16x16x32_bf16 v[12:15], v[172:175], v[180:183], v[12:15]
	v_mfma_f32_16x16x32_bf16 v[8:11], v[168:171], v[184:187], v[8:11]
	v_mfma_f32_16x16x32_bf16 v[8:11], v[172:175], v[188:191], v[8:11]
	v_mfma_f32_16x16x32_bf16 v[4:7], v[168:171], v[192:195], v[4:7]
	v_mfma_f32_16x16x32_bf16 v[4:7], v[172:175], v[196:199], v[4:7]
	v_mfma_f32_16x16x32_bf16 v[0:3], v[168:171], v[200:203], v[0:3]
	v_mfma_f32_16x16x32_bf16 v[0:3], v[172:175], v[204:207], v[0:3]
	s_setprio 0
	s_barrier
	s_nop 1
	s_add_i32 s2, s5, 2
	s_add_u32 s15, s15, 0x100
	s_addc_u32 s75, s75, 0
	s_cmp_gt_u32 s5, 29
	s_mov_b64 s[18:19], s[26:27]
	s_mov_b32 s5, s2
	s_cbranch_scc1 .LBB0_384
	s_branch .LBB0_371

.LBB0_658:
	s_ashr_i32 s75, s74, 31
	s_add_i32 s45, s21, -2
	s_lshl_b64 s[2:3], s[74:75], 20
	s_add_u32 s9, s33, s2
	s_addc_u32 s12, s65, s3
	s_and_b64 s[2:3], s[38:39], exec
	s_cselect_b32 s17, s12, s11
	s_cselect_b32 s16, s9, s10
	s_ashr_i32 s9, s8, 31
	s_lshl_b64 s[2:3], s[8:9], 20
	s_add_u32 s9, s67, s2
	s_addc_u32 s12, s68, s3
	s_and_b64 s[2:3], s[38:39], exec
	s_cselect_b32 s18, s12, s35
	s_cselect_b32 s9, s9, s34
	s_ashr_i32 s41, s40, 31
	s_lshl_b64 s[2:3], s[40:41], 7
	s_and_b64 s[12:13], s[38:39], exec
	s_cselect_b32 s2, s2, 0
	s_cselect_b32 s3, s3, 0
	s_add_u32 s16, s16, s2
	s_addc_u32 s17, s17, s3
	s_add_u32 s12, s9, s2
	s_mul_hi_i32 s2, s42, 0x78787879
	s_addc_u32 s13, s18, s3
	s_lshr_b32 s3, s2, 31
	s_ashr_i32 s2, s2, 3
	s_add_i32 s20, s2, s3
	s_mul_i32 s2, s20, 17
	s_lshl_b32 s18, s44, 8
	s_sub_i32 s2, s42, s2
	s_ashr_i32 s19, s18, 31
	s_cmp_lg_u32 s2, 0
	s_cselect_b32 s2, s20, 8
	s_ashr_i32 s3, s2, 31
	s_lshl_b64 s[22:23], s[2:3], 13
	s_cmp_lg_u32 s21, 32
	s_cselect_b64 s[24:25], -1, 0
	s_cmp_eq_u32 s21, 32
	s_mul_hi_i32 s9, s2, 0xc000
	s_mul_i32 s30, s2, 0xc000
	s_cselect_b64 s[2:3], -1, 0
	s_and_b64 s[26:27], s[58:59], s[2:3]
	s_add_u32 s2, s77, s22
	s_addc_u32 s3, s78, s23
	s_lshl_b64 s[22:23], s[18:19], 2
	s_add_u32 s28, s2, s22
	s_addc_u32 s29, s3, s23
	s_add_u32 s2, s71, s30
	s_addc_u32 s3, s76, s9
	s_add_u32 s30, s2, s22
	s_addc_u32 s31, s3, s23
	s_add_u32 s9, s34, 0x100
	s_addc_u32 s19, s35, 0
	s_add_u32 s2, s10, 0x80080
	s_addc_u32 s3, s11, 0
	s_mov_b32 s41, 0
	v_lshl_add_u64 v[96:97], s[2:3], 0, v[210:211]
	v_lshl_add_u64 v[98:99], s[2:3], 0, v[218:219]
	s_mov_b64 s[34:35], 0
	s_add_i32 s2, s41, 2
	s_add_u32 s3, s10, s34
	s_addc_u32 s50, s11, s35
	s_add_u32 s3, s3, 0x100
	s_addc_u32 s50, s50, 0
	s_add_u32 s51, s9, s34
	s_addc_u32 s75, s19, s35
	s_cmp_eq_u32 s45, s41
	s_cselect_b32 s89, s17, s50
	s_cselect_b32 s88, s16, s3
	s_cselect_b32 vcc_hi, s13, s75
	s_cselect_b32 vcc_lo, s12, s51
	s_add_i32 s3, 0, 0x10000
	s_add_i32 s41, 0, 0x14000
	v_add_u32_e32 v136, s3, v220
	v_add_u32_e32 v160, s41, v220
	ds_read_b128 v[108:111], v136
	ds_read_b128 v[120:123], v136 offset:1024
	ds_read_b128 v[132:135], v136 offset:2048
	ds_read_b128 v[136:139], v136 offset:3072
	ds_read_b128 v[140:143], v160
	ds_read_b128 v[144:147], v160 offset:1024
	ds_read_b128 v[148:151], v160 offset:2048
	ds_read_b128 v[160:163], v160 offset:3072
	v_lshl_add_u64 v[196:197], v[96:97], 0, s[34:35]
	s_add_i32 m0, s15, 0xc000
	ds_read_b128 v[164:167], v223
	ds_read_b128 v[168:171], v223 offset:1024
	ds_read_b128 v[172:175], v223 offset:2048
	ds_read_b128 v[176:179], v223 offset:3072
	ds_read_b128 v[180:183], v223 offset:4096
	ds_read_b128 v[184:187], v223 offset:5120
	ds_read_b128 v[188:191], v223 offset:6144
	ds_read_b128 v[192:195], v223 offset:7168
	global_load_lds_dwordx4 v[196:197], off
	v_lshl_add_u64 v[196:197], v[98:99], 0, s[34:35]
	s_add_i32 m0, s15, 0xe000
	s_nop 0
	global_load_lds_dwordx4 v[196:197], off
	s_waitcnt vmcnt(8)
	s_waitcnt lgkmcnt(0)
	s_barrier
	s_setprio 1
	s_waitcnt lgkmcnt(0)
	v_mfma_f32_16x16x32_bf16 v[156:159], v[108:111], v[164:167], 0
	v_mfma_f32_16x16x32_bf16 v[156:159], v[120:123], v[168:171], v[156:159]
	v_mfma_f32_16x16x32_bf16 v[128:131], v[108:111], v[172:175], 0
	v_mfma_f32_16x16x32_bf16 v[128:131], v[120:123], v[176:179], v[128:131]
	v_mfma_f32_16x16x32_bf16 v[116:119], v[108:111], v[180:183], 0
	v_mfma_f32_16x16x32_bf16 v[116:119], v[120:123], v[184:187], v[116:119]
	v_mfma_f32_16x16x32_bf16 v[104:107], v[108:111], v[188:191], 0
	v_mfma_f32_16x16x32_bf16 v[104:107], v[120:123], v[192:195], v[104:107]
	v_mfma_f32_16x16x32_bf16 v[152:155], v[132:135], v[164:167], 0
	v_mfma_f32_16x16x32_bf16 v[152:155], v[136:139], v[168:171], v[152:155]
	v_mfma_f32_16x16x32_bf16 v[124:127], v[132:135], v[172:175], 0
	v_mfma_f32_16x16x32_bf16 v[124:127], v[136:139], v[176:179], v[124:127]
	v_mfma_f32_16x16x32_bf16 v[112:115], v[132:135], v[180:183], 0
	v_mfma_f32_16x16x32_bf16 v[112:115], v[136:139], v[184:187], v[112:115]
	v_mfma_f32_16x16x32_bf16 v[100:103], v[132:135], v[188:191], 0
	v_mfma_f32_16x16x32_bf16 v[100:103], v[136:139], v[192:195], v[100:103]
	s_setprio 0
	s_setprio 1
	v_mfma_f32_16x16x32_bf16 v[92:95], v[140:143], v[164:167], 0
	v_mfma_f32_16x16x32_bf16 v[92:95], v[144:147], v[168:171], v[92:95]
	v_mfma_f32_16x16x32_bf16 v[84:87], v[140:143], v[172:175], 0
	v_mfma_f32_16x16x32_bf16 v[84:87], v[144:147], v[176:179], v[84:87]
	v_mfma_f32_16x16x32_bf16 v[76:79], v[140:143], v[180:183], 0
	v_mfma_f32_16x16x32_bf16 v[76:79], v[144:147], v[184:187], v[76:79]
	v_mfma_f32_16x16x32_bf16 v[68:71], v[140:143], v[188:191], 0
	v_mfma_f32_16x16x32_bf16 v[68:71], v[144:147], v[192:195], v[68:71]
	v_mfma_f32_16x16x32_bf16 v[88:91], v[148:151], v[164:167], 0
	v_mfma_f32_16x16x32_bf16 v[88:91], v[160:163], v[168:171], v[88:91]
	v_mfma_f32_16x16x32_bf16 v[80:83], v[148:151], v[172:175], 0
	v_mfma_f32_16x16x32_bf16 v[80:83], v[160:163], v[176:179], v[80:83]
	v_mfma_f32_16x16x32_bf16 v[72:75], v[148:151], v[180:183], 0
	v_mfma_f32_16x16x32_bf16 v[72:75], v[160:163], v[184:187], v[72:75]
	v_mfma_f32_16x16x32_bf16 v[64:67], v[148:151], v[188:191], 0
	v_mfma_f32_16x16x32_bf16 v[64:67], v[160:163], v[192:195], v[64:67]
	s_setprio 0
	s_barrier
	s_nop 1
	s_add_i32 s3, s3, s64
	v_lshl_add_u64 v[196:197], vcc, 0, v[212:213]
	s_mov_b32 m0, s3
	ds_read_b128 v[164:167], v223 offset:16384
	ds_read_b128 v[168:171], v223 offset:17408
	ds_read_b128 v[172:175], v223 offset:18432
	ds_read_b128 v[176:179], v223 offset:19456
	ds_read_b128 v[180:183], v223 offset:20480
	ds_read_b128 v[184:187], v223 offset:21504
	ds_read_b128 v[188:191], v223 offset:22528
	ds_read_b128 v[192:195], v223 offset:23552
	global_load_lds_dwordx4 v[196:197], off
	s_add_i32 m0, s3, 0x2000
	s_add_u32 s50, vcc_lo, 0x80000
	v_lshl_add_u64 v[198:199], vcc, 0, v[208:209]
	s_addc_u32 s51, vcc_hi, 0
	s_add_i32 s3, s41, s64
	global_load_lds_dwordx4 v[198:199], off
	v_lshl_add_u64 v[200:201], s[50:51], 0, v[212:213]
	s_mov_b32 m0, s3
	v_lshl_add_u64 v[202:203], s[88:89], 0, v[206:207]
	global_load_lds_dwordx4 v[200:201], off
	v_lshl_add_u64 v[200:201], s[50:51], 0, v[208:209]
	s_add_i32 m0, s3, 0x2000
	s_nop 0
	global_load_lds_dwordx4 v[200:201], off
	v_lshl_add_u64 v[200:201], s[88:89], 0, v[204:205]
	s_mov_b32 m0, s15
	s_nop 0
	global_load_lds_dwordx4 v[200:201], off
	s_mov_b32 m0, s43
	s_nop 0
	global_load_lds_dwordx4 v[202:203], off
	s_waitcnt vmcnt(8)
	s_waitcnt lgkmcnt(0)
	s_barrier
	s_setprio 1
	s_waitcnt lgkmcnt(0)
	v_mfma_f32_16x16x32_bf16 v[60:63], v[108:111], v[164:167], 0
	v_mfma_f32_16x16x32_bf16 v[60:63], v[120:123], v[168:171], v[60:63]
	v_mfma_f32_16x16x32_bf16 v[52:55], v[108:111], v[172:175], 0
	v_mfma_f32_16x16x32_bf16 v[52:55], v[120:123], v[176:179], v[52:55]
	v_mfma_f32_16x16x32_bf16 v[44:47], v[108:111], v[180:183], 0
	v_mfma_f32_16x16x32_bf16 v[44:47], v[120:123], v[184:187], v[44:47]
	v_mfma_f32_16x16x32_bf16 v[36:39], v[108:111], v[188:191], 0
	v_mfma_f32_16x16x32_bf16 v[36:39], v[120:123], v[192:195], v[36:39]
	v_mfma_f32_16x16x32_bf16 v[56:59], v[132:135], v[164:167], 0
	v_mfma_f32_16x16x32_bf16 v[56:59], v[136:139], v[168:171], v[56:59]
	v_mfma_f32_16x16x32_bf16 v[48:51], v[132:135], v[172:175], 0
	v_mfma_f32_16x16x32_bf16 v[48:51], v[136:139], v[176:179], v[48:51]
	v_mfma_f32_16x16x32_bf16 v[40:43], v[132:135], v[180:183], 0
	v_mfma_f32_16x16x32_bf16 v[40:43], v[136:139], v[184:187], v[40:43]
	v_mfma_f32_16x16x32_bf16 v[32:35], v[132:135], v[188:191], 0
	v_mfma_f32_16x16x32_bf16 v[32:35], v[136:139], v[192:195], v[32:35]
	s_setprio 0
	s_setprio 1
	v_mfma_f32_16x16x32_bf16 v[28:31], v[140:143], v[164:167], 0
	v_mfma_f32_16x16x32_bf16 v[28:31], v[144:147], v[168:171], v[28:31]
	v_mfma_f32_16x16x32_bf16 v[20:23], v[140:143], v[172:175], 0
	v_mfma_f32_16x16x32_bf16 v[20:23], v[144:147], v[176:179], v[20:23]
	v_mfma_f32_16x16x32_bf16 v[12:15], v[140:143], v[180:183], 0
	v_mfma_f32_16x16x32_bf16 v[12:15], v[144:147], v[184:187], v[12:15]
	v_mfma_f32_16x16x32_bf16 v[4:7], v[140:143], v[188:191], 0
	v_mfma_f32_16x16x32_bf16 v[4:7], v[144:147], v[192:195], v[4:7]
	v_mfma_f32_16x16x32_bf16 v[24:27], v[148:151], v[164:167], 0
	v_mfma_f32_16x16x32_bf16 v[24:27], v[160:163], v[168:171], v[24:27]
	v_mfma_f32_16x16x32_bf16 v[16:19], v[148:151], v[172:175], 0
	v_mfma_f32_16x16x32_bf16 v[16:19], v[160:163], v[176:179], v[16:19]
	v_mfma_f32_16x16x32_bf16 v[8:11], v[148:151], v[180:183], 0
	v_mfma_f32_16x16x32_bf16 v[8:11], v[160:163], v[184:187], v[8:11]
	v_mfma_f32_16x16x32_bf16 v[0:3], v[148:151], v[188:191], 0
	v_mfma_f32_16x16x32_bf16 v[0:3], v[160:163], v[192:195], v[0:3]
	s_setprio 0
	s_barrier
	s_nop 1
	s_add_i32 s3, 0, 0x18000
	s_add_i32 s41, 0, 0x1c000
	v_add_u32_e32 v136, s3, v220
	v_add_u32_e32 v160, s41, v220
	ds_read_b128 v[108:111], v136
	ds_read_b128 v[120:123], v136 offset:1024
	ds_read_b128 v[132:135], v136 offset:2048
	ds_read_b128 v[136:139], v136 offset:3072
	ds_read_b128 v[140:143], v160
	ds_read_b128 v[144:147], v160 offset:1024
	ds_read_b128 v[148:151], v160 offset:2048
	ds_read_b128 v[160:163], v160 offset:3072
	s_add_u32 s50, s88, 0x80000
	s_addc_u32 s51, s89, 0
	s_mov_b32 m0, s69
	v_lshl_add_u64 v[214:215], s[50:51], 0, v[204:205]
	ds_read_b128 v[164:167], v223 offset:32768
	ds_read_b128 v[168:171], v223 offset:33792
	ds_read_b128 v[172:175], v223 offset:34816
	ds_read_b128 v[176:179], v223 offset:35840
	ds_read_b128 v[180:183], v223 offset:36864
	ds_read_b128 v[184:187], v223 offset:37888
	ds_read_b128 v[188:191], v223 offset:38912
	ds_read_b128 v[192:195], v223 offset:39936
	global_load_lds_dwordx4 v[214:215], off
	v_lshl_add_u64 v[214:215], s[50:51], 0, v[206:207]
	s_mov_b32 m0, s70
	s_nop 0
	global_load_lds_dwordx4 v[214:215], off
	s_waitcnt vmcnt(8)
	s_waitcnt lgkmcnt(0)
	s_barrier
	s_setprio 1
	s_waitcnt lgkmcnt(0)
	v_mfma_f32_16x16x32_bf16 v[156:159], v[108:111], v[164:167], v[156:159]
	v_mfma_f32_16x16x32_bf16 v[156:159], v[120:123], v[168:171], v[156:159]
	v_mfma_f32_16x16x32_bf16 v[128:131], v[108:111], v[172:175], v[128:131]
	v_mfma_f32_16x16x32_bf16 v[128:131], v[120:123], v[176:179], v[128:131]
	v_mfma_f32_16x16x32_bf16 v[116:119], v[108:111], v[180:183], v[116:119]
	v_mfma_f32_16x16x32_bf16 v[116:119], v[120:123], v[184:187], v[116:119]
	v_mfma_f32_16x16x32_bf16 v[104:107], v[108:111], v[188:191], v[104:107]
	v_mfma_f32_16x16x32_bf16 v[104:107], v[120:123], v[192:195], v[104:107]
	v_mfma_f32_16x16x32_bf16 v[152:155], v[132:135], v[164:167], v[152:155]
	v_mfma_f32_16x16x32_bf16 v[152:155], v[136:139], v[168:171], v[152:155]
	v_mfma_f32_16x16x32_bf16 v[124:127], v[132:135], v[172:175], v[124:127]
	v_mfma_f32_16x16x32_bf16 v[124:127], v[136:139], v[176:179], v[124:127]
	v_mfma_f32_16x16x32_bf16 v[112:115], v[132:135], v[180:183], v[112:115]
	v_mfma_f32_16x16x32_bf16 v[112:115], v[136:139], v[184:187], v[112:115]
	v_mfma_f32_16x16x32_bf16 v[100:103], v[132:135], v[188:191], v[100:103]
	v_mfma_f32_16x16x32_bf16 v[100:103], v[136:139], v[192:195], v[100:103]
	s_setprio 0
	s_setprio 1
	v_mfma_f32_16x16x32_bf16 v[92:95], v[140:143], v[164:167], v[92:95]
	v_mfma_f32_16x16x32_bf16 v[92:95], v[144:147], v[168:171], v[92:95]
	v_mfma_f32_16x16x32_bf16 v[84:87], v[140:143], v[172:175], v[84:87]
	v_mfma_f32_16x16x32_bf16 v[84:87], v[144:147], v[176:179], v[84:87]
	v_mfma_f32_16x16x32_bf16 v[76:79], v[140:143], v[180:183], v[76:79]
	v_mfma_f32_16x16x32_bf16 v[76:79], v[144:147], v[184:187], v[76:79]
	v_mfma_f32_16x16x32_bf16 v[68:71], v[140:143], v[188:191], v[68:71]
	v_mfma_f32_16x16x32_bf16 v[68:71], v[144:147], v[192:195], v[68:71]
	v_mfma_f32_16x16x32_bf16 v[88:91], v[148:151], v[164:167], v[88:91]
	v_mfma_f32_16x16x32_bf16 v[88:91], v[160:163], v[168:171], v[88:91]
	v_mfma_f32_16x16x32_bf16 v[80:83], v[148:151], v[172:175], v[80:83]
	v_mfma_f32_16x16x32_bf16 v[80:83], v[160:163], v[176:179], v[80:83]
	v_mfma_f32_16x16x32_bf16 v[72:75], v[148:151], v[180:183], v[72:75]
	v_mfma_f32_16x16x32_bf16 v[72:75], v[160:163], v[184:187], v[72:75]
	v_mfma_f32_16x16x32_bf16 v[64:67], v[148:151], v[188:191], v[64:67]
	v_mfma_f32_16x16x32_bf16 v[64:67], v[160:163], v[192:195], v[64:67]
	s_setprio 0
	s_barrier
	s_nop 1
	s_add_i32 s3, s3, s64
	v_lshl_add_u64 v[196:197], v[196:197], 0, s[72:73]
	s_mov_b32 m0, s3
	ds_read_b128 v[164:167], v223 offset:49152
	ds_read_b128 v[168:171], v223 offset:50176
	ds_read_b128 v[172:175], v223 offset:51200
	ds_read_b128 v[176:179], v223 offset:52224
	ds_read_b128 v[180:183], v223 offset:53248
	ds_read_b128 v[184:187], v223 offset:54272
	ds_read_b128 v[188:191], v223 offset:55296
	ds_read_b128 v[192:195], v223 offset:56320
	global_load_lds_dwordx4 v[196:197], off
	s_add_i32 m0, s3, 0x2000
	s_add_u32 s50, vcc_lo, 0x80080
	v_lshl_add_u64 v[196:197], v[198:199], 0, s[72:73]
	s_addc_u32 s51, vcc_hi, 0
	s_add_i32 s3, s41, s64
	global_load_lds_dwordx4 v[196:197], off
	v_lshl_add_u64 v[196:197], s[50:51], 0, v[212:213]
	s_mov_b32 m0, s3
	s_nop 0
	global_load_lds_dwordx4 v[196:197], off
	v_lshl_add_u64 v[196:197], s[50:51], 0, v[208:209]
	s_add_i32 m0, s3, 0x2000
	s_nop 0
	global_load_lds_dwordx4 v[196:197], off
	v_lshl_add_u64 v[196:197], v[200:201], 0, s[72:73]
	s_mov_b32 m0, s83
	s_nop 0
	global_load_lds_dwordx4 v[196:197], off
	v_lshl_add_u64 v[196:197], v[202:203], 0, s[72:73]
	s_mov_b32 m0, s84
	s_nop 0
	global_load_lds_dwordx4 v[196:197], off
	s_waitcnt vmcnt(8)
	s_waitcnt lgkmcnt(0)
	s_barrier
	s_setprio 1
	s_waitcnt lgkmcnt(0)
	v_mfma_f32_16x16x32_bf16 v[60:63], v[108:111], v[164:167], v[60:63]
	v_mfma_f32_16x16x32_bf16 v[60:63], v[120:123], v[168:171], v[60:63]
	v_mfma_f32_16x16x32_bf16 v[52:55], v[108:111], v[172:175], v[52:55]
	v_mfma_f32_16x16x32_bf16 v[52:55], v[120:123], v[176:179], v[52:55]
	v_mfma_f32_16x16x32_bf16 v[44:47], v[108:111], v[180:183], v[44:47]
	v_mfma_f32_16x16x32_bf16 v[44:47], v[120:123], v[184:187], v[44:47]
	v_mfma_f32_16x16x32_bf16 v[36:39], v[108:111], v[188:191], v[36:39]
	v_mfma_f32_16x16x32_bf16 v[36:39], v[120:123], v[192:195], v[36:39]
	v_mfma_f32_16x16x32_bf16 v[56:59], v[132:135], v[164:167], v[56:59]
	v_mfma_f32_16x16x32_bf16 v[56:59], v[136:139], v[168:171], v[56:59]
	v_mfma_f32_16x16x32_bf16 v[48:51], v[132:135], v[172:175], v[48:51]
	v_mfma_f32_16x16x32_bf16 v[48:51], v[136:139], v[176:179], v[48:51]
	v_mfma_f32_16x16x32_bf16 v[40:43], v[132:135], v[180:183], v[40:43]
	v_mfma_f32_16x16x32_bf16 v[40:43], v[136:139], v[184:187], v[40:43]
	v_mfma_f32_16x16x32_bf16 v[32:35], v[132:135], v[188:191], v[32:35]
	v_mfma_f32_16x16x32_bf16 v[32:35], v[136:139], v[192:195], v[32:35]
	s_setprio 0
	s_setprio 1
	v_mfma_f32_16x16x32_bf16 v[28:31], v[140:143], v[164:167], v[28:31]
	v_mfma_f32_16x16x32_bf16 v[28:31], v[144:147], v[168:171], v[28:31]
	v_mfma_f32_16x16x32_bf16 v[20:23], v[140:143], v[172:175], v[20:23]
	v_mfma_f32_16x16x32_bf16 v[20:23], v[144:147], v[176:179], v[20:23]
	v_mfma_f32_16x16x32_bf16 v[12:15], v[140:143], v[180:183], v[12:15]
	v_mfma_f32_16x16x32_bf16 v[12:15], v[144:147], v[184:187], v[12:15]
	v_mfma_f32_16x16x32_bf16 v[4:7], v[140:143], v[188:191], v[4:7]
	v_mfma_f32_16x16x32_bf16 v[4:7], v[144:147], v[192:195], v[4:7]
	v_mfma_f32_16x16x32_bf16 v[24:27], v[148:151], v[164:167], v[24:27]
	v_mfma_f32_16x16x32_bf16 v[24:27], v[160:163], v[168:171], v[24:27]
	v_mfma_f32_16x16x32_bf16 v[16:19], v[148:151], v[172:175], v[16:19]
	v_mfma_f32_16x16x32_bf16 v[16:19], v[160:163], v[176:179], v[16:19]
	v_mfma_f32_16x16x32_bf16 v[8:11], v[148:151], v[180:183], v[8:11]
	v_mfma_f32_16x16x32_bf16 v[8:11], v[160:163], v[184:187], v[8:11]
	v_mfma_f32_16x16x32_bf16 v[0:3], v[148:151], v[188:191], v[0:3]
	v_mfma_f32_16x16x32_bf16 v[0:3], v[160:163], v[192:195], v[0:3]
	s_setprio 0
	s_barrier
	s_nop 1
	s_add_u32 s34, s34, 0x100
	s_addc_u32 s35, s35, 0
	s_cmp_ge_i32 s2, s21
	s_mov_b32 s41, s2
	s_cbranch_scc1 .LBB0_666
	s_branch .LBB0_660

.LBB0_830:
	s_ashr_i32 s13, s12, 31
	s_lshl_b64 s[2:3], s[12:13], 20
	s_add_u32 s14, s33, s2
	s_addc_u32 s15, s34, s3
	s_and_b64 s[2:3], s[36:37], exec
	s_cselect_b32 s13, s15, s25
	s_cselect_b32 s63, s14, s24
	s_ashr_i32 s11, s10, 31
	s_lshl_b64 s[2:3], s[10:11], 20
	s_add_u32 s38, s35, s2
	s_addc_u32 s39, s40, s3
	s_and_b64 s[2:3], s[36:37], exec
	s_cselect_b32 s11, s39, s27
	s_cselect_b32 s64, s38, s26
	s_lshl_b32 s16, s18, 8
	s_ashr_i32 s17, s16, 31
	s_lshl_b64 s[2:3], s[16:17], 5
	s_mul_hi_i32 s17, s18, 0x78787879
	s_lshr_b32 s20, s17, 31
	s_ashr_i32 s17, s17, 3
	s_add_i32 s17, s17, s20
	s_mul_i32 s20, s17, 17
	s_sub_i32 s20, s18, s20
	s_lshl_b32 s18, s19, 8
	s_ashr_i32 s19, s18, 31
	s_mul_i32 s21, s17, 0xf400
	s_mul_hi_i32 s22, s17, 0xf400
	s_cmp_lg_u32 s20, 0
	s_cselect_b32 s23, s22, 0
	s_cselect_b32 s22, s21, 0x7a000
	s_add_u32 s20, s47, s2
	s_addc_u32 s21, s49, s3
	s_lshl_b64 s[2:3], s[22:23], 2
	s_add_u32 s22, s50, s2
	s_addc_u32 s23, s51, s3
	s_lshl_b64 s[2:3], s[18:19], 2
	s_add_u32 s22, s22, s2
	s_addc_u32 s23, s23, s3
	s_add_u32 s24, s24, 0x80080
	s_addc_u32 s25, s25, 0
	s_add_u32 s19, s26, 0x100
	s_mov_b32 s17, 0
	s_addc_u32 s65, s27, 0
	s_add_u32 s2, s24, 0xfff80080
	s_addc_u32 s3, s25, -1
	s_cmp_eq_u32 s17, 30
	s_cselect_b32 s29, s13, s3
	s_cselect_b32 s28, s63, s2
	s_cselect_b32 s27, s11, s65
	s_cselect_b32 s26, s64, s19
	s_add_i32 s2, 0, 0x10000
	v_add_u32_e32 v138, s2, v140
	s_add_i32 s66, 0, 0x14000
	ds_read_b128 v[142:145], v138
	ds_read_b128 v[146:149], v138 offset:1024
	ds_read_b128 v[150:153], v138 offset:2048
	ds_read_b128 v[154:157], v138 offset:3072
	v_add_u32_e32 v138, s66, v140
	ds_read_b128 v[158:161], v138
	ds_read_b128 v[162:165], v138 offset:1024
	ds_read_b128 v[166:169], v138 offset:2048
	ds_read_b128 v[170:173], v138 offset:3072
	v_lshl_add_u64 v[138:139], s[24:25], 0, v[134:135]
	s_add_i32 m0, s43, 0xc000
	ds_read_b128 v[174:177], v141
	ds_read_b128 v[178:181], v141 offset:1024
	ds_read_b128 v[182:185], v141 offset:2048
	ds_read_b128 v[186:189], v141 offset:3072
	ds_read_b128 v[190:193], v141 offset:4096
	ds_read_b128 v[194:197], v141 offset:5120
	ds_read_b128 v[198:201], v141 offset:6144
	ds_read_b128 v[202:205], v141 offset:7168
	global_load_lds_dwordx4 v[138:139], off
	v_lshl_add_u64 v[138:139], s[24:25], 0, v[136:137]
	s_add_i32 m0, s43, 0xe000
	s_nop 0
	global_load_lds_dwordx4 v[138:139], off
	s_waitcnt vmcnt(8)
	s_waitcnt lgkmcnt(0)
	s_barrier
	s_setprio 1
	s_waitcnt lgkmcnt(0)
	v_mfma_f32_16x16x32_bf16 v[124:127], v[142:145], v[174:177], 0
	v_mfma_f32_16x16x32_bf16 v[124:127], v[146:149], v[178:181], v[124:127]
	v_mfma_f32_16x16x32_bf16 v[120:123], v[142:145], v[182:185], 0
	v_mfma_f32_16x16x32_bf16 v[120:123], v[146:149], v[186:189], v[120:123]
	v_mfma_f32_16x16x32_bf16 v[116:119], v[142:145], v[190:193], 0
	v_mfma_f32_16x16x32_bf16 v[116:119], v[146:149], v[194:197], v[116:119]
	v_mfma_f32_16x16x32_bf16 v[112:115], v[142:145], v[198:201], 0
	v_mfma_f32_16x16x32_bf16 v[112:115], v[146:149], v[202:205], v[112:115]
	v_mfma_f32_16x16x32_bf16 v[108:111], v[150:153], v[174:177], 0
	v_mfma_f32_16x16x32_bf16 v[108:111], v[154:157], v[178:181], v[108:111]
	v_mfma_f32_16x16x32_bf16 v[104:107], v[150:153], v[182:185], 0
	v_mfma_f32_16x16x32_bf16 v[104:107], v[154:157], v[186:189], v[104:107]
	v_mfma_f32_16x16x32_bf16 v[100:103], v[150:153], v[190:193], 0
	v_mfma_f32_16x16x32_bf16 v[100:103], v[154:157], v[194:197], v[100:103]
	v_mfma_f32_16x16x32_bf16 v[96:99], v[150:153], v[198:201], 0
	v_mfma_f32_16x16x32_bf16 v[96:99], v[154:157], v[202:205], v[96:99]
	s_setprio 0
	s_setprio 1
	v_mfma_f32_16x16x32_bf16 v[84:87], v[158:161], v[174:177], 0
	v_mfma_f32_16x16x32_bf16 v[84:87], v[162:165], v[178:181], v[84:87]
	v_mfma_f32_16x16x32_bf16 v[76:79], v[158:161], v[182:185], 0
	v_mfma_f32_16x16x32_bf16 v[76:79], v[162:165], v[186:189], v[76:79]
	v_mfma_f32_16x16x32_bf16 v[64:67], v[158:161], v[190:193], 0
	v_mfma_f32_16x16x32_bf16 v[64:67], v[162:165], v[194:197], v[64:67]
	v_mfma_f32_16x16x32_bf16 v[56:59], v[158:161], v[198:201], 0
	v_mfma_f32_16x16x32_bf16 v[56:59], v[162:165], v[202:205], v[56:59]
	v_mfma_f32_16x16x32_bf16 v[52:55], v[166:169], v[174:177], 0
	v_mfma_f32_16x16x32_bf16 v[52:55], v[170:173], v[178:181], v[52:55]
	v_mfma_f32_16x16x32_bf16 v[44:47], v[166:169], v[182:185], 0
	v_mfma_f32_16x16x32_bf16 v[44:47], v[170:173], v[186:189], v[44:47]
	v_mfma_f32_16x16x32_bf16 v[36:39], v[166:169], v[190:193], 0
	v_mfma_f32_16x16x32_bf16 v[36:39], v[170:173], v[194:197], v[36:39]
	v_mfma_f32_16x16x32_bf16 v[32:35], v[166:169], v[198:201], 0
	v_mfma_f32_16x16x32_bf16 v[32:35], v[170:173], v[202:205], v[32:35]
	s_setprio 0
	s_barrier
	s_nop 1
	s_add_i32 s2, s2, s41
	v_lshl_add_u64 v[138:139], s[26:27], 0, v[212:213]
	s_mov_b32 m0, s2
	ds_read_b128 v[174:177], v141 offset:16384
	ds_read_b128 v[178:181], v141 offset:17408
	ds_read_b128 v[182:185], v141 offset:18432
	ds_read_b128 v[186:189], v141 offset:19456
	ds_read_b128 v[190:193], v141 offset:20480
	ds_read_b128 v[194:197], v141 offset:21504
	ds_read_b128 v[198:201], v141 offset:22528
	ds_read_b128 v[202:205], v141 offset:23552
	global_load_lds_dwordx4 v[138:139], off
	s_add_i32 m0, s2, 0x2000
	s_add_u32 s2, s26, 0x80000
	v_lshl_add_u64 v[206:207], s[26:27], 0, v[128:129]
	s_addc_u32 s3, s27, 0
	s_add_i32 s66, s66, s41
	global_load_lds_dwordx4 v[206:207], off
	v_lshl_add_u64 v[208:209], s[2:3], 0, v[212:213]
	s_mov_b32 m0, s66
	v_lshl_add_u64 v[210:211], s[28:29], 0, v[130:131]
	global_load_lds_dwordx4 v[208:209], off
	v_lshl_add_u64 v[208:209], s[2:3], 0, v[128:129]
	s_add_i32 m0, s66, 0x2000
	s_nop 0
	global_load_lds_dwordx4 v[208:209], off
	v_lshl_add_u64 v[208:209], s[28:29], 0, v[132:133]
	s_mov_b32 m0, s43
	s_nop 0
	global_load_lds_dwordx4 v[208:209], off
	s_mov_b32 m0, s44
	s_nop 0
	global_load_lds_dwordx4 v[210:211], off
	s_waitcnt vmcnt(8)
	s_waitcnt lgkmcnt(0)
	s_barrier
	s_setprio 1
	s_waitcnt lgkmcnt(0)
	v_mfma_f32_16x16x32_bf16 v[92:95], v[142:145], v[174:177], 0
	v_mfma_f32_16x16x32_bf16 v[92:95], v[146:149], v[178:181], v[92:95]
	v_mfma_f32_16x16x32_bf16 v[88:91], v[142:145], v[182:185], 0
	v_mfma_f32_16x16x32_bf16 v[88:91], v[146:149], v[186:189], v[88:91]
	v_mfma_f32_16x16x32_bf16 v[80:83], v[142:145], v[190:193], 0
	v_mfma_f32_16x16x32_bf16 v[80:83], v[146:149], v[194:197], v[80:83]
	v_mfma_f32_16x16x32_bf16 v[72:75], v[142:145], v[198:201], 0
	v_mfma_f32_16x16x32_bf16 v[72:75], v[146:149], v[202:205], v[72:75]
	v_mfma_f32_16x16x32_bf16 v[68:71], v[150:153], v[174:177], 0
	v_mfma_f32_16x16x32_bf16 v[68:71], v[154:157], v[178:181], v[68:71]
	v_mfma_f32_16x16x32_bf16 v[60:63], v[150:153], v[182:185], 0
	v_mfma_f32_16x16x32_bf16 v[60:63], v[154:157], v[186:189], v[60:63]
	v_mfma_f32_16x16x32_bf16 v[48:51], v[150:153], v[190:193], 0
	v_mfma_f32_16x16x32_bf16 v[48:51], v[154:157], v[194:197], v[48:51]
	v_mfma_f32_16x16x32_bf16 v[40:43], v[150:153], v[198:201], 0
	v_mfma_f32_16x16x32_bf16 v[40:43], v[154:157], v[202:205], v[40:43]
	s_setprio 0
	s_setprio 1
	v_mfma_f32_16x16x32_bf16 v[28:31], v[158:161], v[174:177], 0
	v_mfma_f32_16x16x32_bf16 v[28:31], v[162:165], v[178:181], v[28:31]
	v_mfma_f32_16x16x32_bf16 v[24:27], v[158:161], v[182:185], 0
	v_mfma_f32_16x16x32_bf16 v[24:27], v[162:165], v[186:189], v[24:27]
	v_mfma_f32_16x16x32_bf16 v[20:23], v[158:161], v[190:193], 0
	v_mfma_f32_16x16x32_bf16 v[20:23], v[162:165], v[194:197], v[20:23]
	v_mfma_f32_16x16x32_bf16 v[16:19], v[158:161], v[198:201], 0
	v_mfma_f32_16x16x32_bf16 v[16:19], v[162:165], v[202:205], v[16:19]
	v_mfma_f32_16x16x32_bf16 v[12:15], v[166:169], v[174:177], 0
	v_mfma_f32_16x16x32_bf16 v[12:15], v[170:173], v[178:181], v[12:15]
	v_mfma_f32_16x16x32_bf16 v[8:11], v[166:169], v[182:185], 0
	v_mfma_f32_16x16x32_bf16 v[8:11], v[170:173], v[186:189], v[8:11]
	v_mfma_f32_16x16x32_bf16 v[4:7], v[166:169], v[190:193], 0
	v_mfma_f32_16x16x32_bf16 v[4:7], v[170:173], v[194:197], v[4:7]
	v_mfma_f32_16x16x32_bf16 v[0:3], v[166:169], v[198:201], 0
	v_mfma_f32_16x16x32_bf16 v[0:3], v[170:173], v[202:205], v[0:3]
	s_setprio 0
	s_barrier
	s_nop 1
	s_add_i32 s66, 0, 0x18000
	s_add_i32 s67, 0, 0x1c000
	v_add_u32_e32 v154, s66, v140
	v_add_u32_e32 v170, s67, v140
	ds_read_b128 v[142:145], v154
	ds_read_b128 v[146:149], v154 offset:1024
	ds_read_b128 v[150:153], v154 offset:2048
	ds_read_b128 v[154:157], v154 offset:3072
	ds_read_b128 v[158:161], v170
	ds_read_b128 v[162:165], v170 offset:1024
	ds_read_b128 v[166:169], v170 offset:2048
	ds_read_b128 v[170:173], v170 offset:3072
	s_add_u32 s2, s28, 0x80000
	s_addc_u32 s3, s29, 0
	s_mov_b32 m0, s45
	v_lshl_add_u64 v[214:215], s[2:3], 0, v[132:133]
	ds_read_b128 v[174:177], v141 offset:32768
	ds_read_b128 v[178:181], v141 offset:33792
	ds_read_b128 v[182:185], v141 offset:34816
	ds_read_b128 v[186:189], v141 offset:35840
	ds_read_b128 v[190:193], v141 offset:36864
	ds_read_b128 v[194:197], v141 offset:37888
	ds_read_b128 v[198:201], v141 offset:38912
	ds_read_b128 v[202:205], v141 offset:39936
	global_load_lds_dwordx4 v[214:215], off
	v_lshl_add_u64 v[214:215], s[2:3], 0, v[130:131]
	s_mov_b32 m0, s46
	s_nop 0
	global_load_lds_dwordx4 v[214:215], off
	s_waitcnt vmcnt(8)
	s_waitcnt lgkmcnt(0)
	s_barrier
	s_setprio 1
	s_waitcnt lgkmcnt(0)
	v_mfma_f32_16x16x32_bf16 v[124:127], v[142:145], v[174:177], v[124:127]
	v_mfma_f32_16x16x32_bf16 v[124:127], v[146:149], v[178:181], v[124:127]
	v_mfma_f32_16x16x32_bf16 v[120:123], v[142:145], v[182:185], v[120:123]
	v_mfma_f32_16x16x32_bf16 v[120:123], v[146:149], v[186:189], v[120:123]
	v_mfma_f32_16x16x32_bf16 v[116:119], v[142:145], v[190:193], v[116:119]
	v_mfma_f32_16x16x32_bf16 v[116:119], v[146:149], v[194:197], v[116:119]
	v_mfma_f32_16x16x32_bf16 v[112:115], v[142:145], v[198:201], v[112:115]
	v_mfma_f32_16x16x32_bf16 v[112:115], v[146:149], v[202:205], v[112:115]
	v_mfma_f32_16x16x32_bf16 v[108:111], v[150:153], v[174:177], v[108:111]
	v_mfma_f32_16x16x32_bf16 v[108:111], v[154:157], v[178:181], v[108:111]
	v_mfma_f32_16x16x32_bf16 v[104:107], v[150:153], v[182:185], v[104:107]
	v_mfma_f32_16x16x32_bf16 v[104:107], v[154:157], v[186:189], v[104:107]
	v_mfma_f32_16x16x32_bf16 v[100:103], v[150:153], v[190:193], v[100:103]
	v_mfma_f32_16x16x32_bf16 v[100:103], v[154:157], v[194:197], v[100:103]
	v_mfma_f32_16x16x32_bf16 v[96:99], v[150:153], v[198:201], v[96:99]
	v_mfma_f32_16x16x32_bf16 v[96:99], v[154:157], v[202:205], v[96:99]
	s_setprio 0
	s_setprio 1
	v_mfma_f32_16x16x32_bf16 v[84:87], v[158:161], v[174:177], v[84:87]
	v_mfma_f32_16x16x32_bf16 v[84:87], v[162:165], v[178:181], v[84:87]
	v_mfma_f32_16x16x32_bf16 v[76:79], v[158:161], v[182:185], v[76:79]
	v_mfma_f32_16x16x32_bf16 v[76:79], v[162:165], v[186:189], v[76:79]
	v_mfma_f32_16x16x32_bf16 v[64:67], v[158:161], v[190:193], v[64:67]
	v_mfma_f32_16x16x32_bf16 v[64:67], v[162:165], v[194:197], v[64:67]
	v_mfma_f32_16x16x32_bf16 v[56:59], v[158:161], v[198:201], v[56:59]
	v_mfma_f32_16x16x32_bf16 v[56:59], v[162:165], v[202:205], v[56:59]
	v_mfma_f32_16x16x32_bf16 v[52:55], v[166:169], v[174:177], v[52:55]
	v_mfma_f32_16x16x32_bf16 v[52:55], v[170:173], v[178:181], v[52:55]
	v_mfma_f32_16x16x32_bf16 v[44:47], v[166:169], v[182:185], v[44:47]
	v_mfma_f32_16x16x32_bf16 v[44:47], v[170:173], v[186:189], v[44:47]
	v_mfma_f32_16x16x32_bf16 v[36:39], v[166:169], v[190:193], v[36:39]
	v_mfma_f32_16x16x32_bf16 v[36:39], v[170:173], v[194:197], v[36:39]
	v_mfma_f32_16x16x32_bf16 v[32:35], v[166:169], v[198:201], v[32:35]
	v_mfma_f32_16x16x32_bf16 v[32:35], v[170:173], v[202:205], v[32:35]
	s_setprio 0
	s_barrier
	s_nop 1
	s_add_i32 s2, s66, s41
	v_lshl_add_u64 v[138:139], v[138:139], 0, s[72:73]
	s_mov_b32 m0, s2
	ds_read_b128 v[174:177], v141 offset:49152
	ds_read_b128 v[178:181], v141 offset:50176
	ds_read_b128 v[182:185], v141 offset:51200
	ds_read_b128 v[186:189], v141 offset:52224
	ds_read_b128 v[190:193], v141 offset:53248
	ds_read_b128 v[194:197], v141 offset:54272
	ds_read_b128 v[198:201], v141 offset:55296
	ds_read_b128 v[202:205], v141 offset:56320
	global_load_lds_dwordx4 v[138:139], off
	s_add_i32 m0, s2, 0x2000
	s_add_u32 s2, s26, 0x80080
	v_lshl_add_u64 v[138:139], v[206:207], 0, s[72:73]
	s_addc_u32 s3, s27, 0
	s_add_i32 s26, s67, s41
	global_load_lds_dwordx4 v[138:139], off
	v_lshl_add_u64 v[138:139], s[2:3], 0, v[212:213]
	s_mov_b32 m0, s26
	s_nop 0
	global_load_lds_dwordx4 v[138:139], off
	v_lshl_add_u64 v[138:139], s[2:3], 0, v[128:129]
	s_add_i32 m0, s26, 0x2000
	s_nop 0
	global_load_lds_dwordx4 v[138:139], off
	v_lshl_add_u64 v[138:139], v[208:209], 0, s[72:73]
	s_mov_b32 m0, s54
	s_nop 0
	global_load_lds_dwordx4 v[138:139], off
	v_lshl_add_u64 v[138:139], v[210:211], 0, s[72:73]
	s_mov_b32 m0, s55
	s_nop 0
	global_load_lds_dwordx4 v[138:139], off
	s_waitcnt vmcnt(8)
	s_waitcnt lgkmcnt(0)
	s_barrier
	s_setprio 1
	s_waitcnt lgkmcnt(0)
	v_mfma_f32_16x16x32_bf16 v[92:95], v[142:145], v[174:177], v[92:95]
	v_mfma_f32_16x16x32_bf16 v[92:95], v[146:149], v[178:181], v[92:95]
	v_mfma_f32_16x16x32_bf16 v[88:91], v[142:145], v[182:185], v[88:91]
	v_mfma_f32_16x16x32_bf16 v[88:91], v[146:149], v[186:189], v[88:91]
	v_mfma_f32_16x16x32_bf16 v[80:83], v[142:145], v[190:193], v[80:83]
	v_mfma_f32_16x16x32_bf16 v[80:83], v[146:149], v[194:197], v[80:83]
	v_mfma_f32_16x16x32_bf16 v[72:75], v[142:145], v[198:201], v[72:75]
	v_mfma_f32_16x16x32_bf16 v[72:75], v[146:149], v[202:205], v[72:75]
	v_mfma_f32_16x16x32_bf16 v[68:71], v[150:153], v[174:177], v[68:71]
	v_mfma_f32_16x16x32_bf16 v[68:71], v[154:157], v[178:181], v[68:71]
	v_mfma_f32_16x16x32_bf16 v[60:63], v[150:153], v[182:185], v[60:63]
	v_mfma_f32_16x16x32_bf16 v[60:63], v[154:157], v[186:189], v[60:63]
	v_mfma_f32_16x16x32_bf16 v[48:51], v[150:153], v[190:193], v[48:51]
	v_mfma_f32_16x16x32_bf16 v[48:51], v[154:157], v[194:197], v[48:51]
	v_mfma_f32_16x16x32_bf16 v[40:43], v[150:153], v[198:201], v[40:43]
	v_mfma_f32_16x16x32_bf16 v[40:43], v[154:157], v[202:205], v[40:43]
	s_setprio 0
	s_setprio 1
	v_mfma_f32_16x16x32_bf16 v[28:31], v[158:161], v[174:177], v[28:31]
	v_mfma_f32_16x16x32_bf16 v[28:31], v[162:165], v[178:181], v[28:31]
	v_mfma_f32_16x16x32_bf16 v[24:27], v[158:161], v[182:185], v[24:27]
	v_mfma_f32_16x16x32_bf16 v[24:27], v[162:165], v[186:189], v[24:27]
	v_mfma_f32_16x16x32_bf16 v[20:23], v[158:161], v[190:193], v[20:23]
	v_mfma_f32_16x16x32_bf16 v[20:23], v[162:165], v[194:197], v[20:23]
	v_mfma_f32_16x16x32_bf16 v[16:19], v[158:161], v[198:201], v[16:19]
	v_mfma_f32_16x16x32_bf16 v[16:19], v[162:165], v[202:205], v[16:19]
	v_mfma_f32_16x16x32_bf16 v[12:15], v[166:169], v[174:177], v[12:15]
	v_mfma_f32_16x16x32_bf16 v[12:15], v[170:173], v[178:181], v[12:15]
	v_mfma_f32_16x16x32_bf16 v[8:11], v[166:169], v[182:185], v[8:11]
	v_mfma_f32_16x16x32_bf16 v[8:11], v[170:173], v[186:189], v[8:11]
	v_mfma_f32_16x16x32_bf16 v[4:7], v[166:169], v[190:193], v[4:7]
	v_mfma_f32_16x16x32_bf16 v[4:7], v[170:173], v[194:197], v[4:7]
	v_mfma_f32_16x16x32_bf16 v[0:3], v[166:169], v[198:201], v[0:3]
	v_mfma_f32_16x16x32_bf16 v[0:3], v[170:173], v[202:205], v[0:3]
	s_setprio 0
	s_barrier
	s_nop 1
	s_add_i32 s2, s17, 2
	s_add_u32 s24, s24, 0x100
	s_addc_u32 s25, s25, 0
	s_add_u32 s19, s19, 0x100
	s_addc_u32 s65, s65, 0
	s_cmp_gt_u32 s17, 29
	s_mov_b32 s17, s2
	s_cbranch_scc1 .LBB0_842
	s_branch .LBB0_832

.LBB0_1238:
	s_ashr_i32 s63, s62, 31
	s_add_i32 s45, s19, -2
	s_lshl_b64 s[2:3], s[62:63], 20
	s_add_u32 s9, s33, s2
	s_addc_u32 s10, s65, s3
	s_and_b64 s[2:3], s[36:37], exec
	s_cselect_b32 s12, s10, s75
	s_cselect_b32 s13, s9, s74
	s_ashr_i32 s9, s8, 31
	s_lshl_b64 s[2:3], s[8:9], 20
	s_add_u32 s9, s67, s2
	s_addc_u32 s10, s68, s3
	s_and_b64 s[2:3], s[36:37], exec
	s_cselect_b32 s16, s10, s31
	s_cselect_b32 s9, s9, s30
	s_ashr_i32 s39, s38, 31
	s_lshl_b64 s[2:3], s[38:39], 7
	s_and_b64 s[10:11], s[36:37], exec
	s_cselect_b32 s2, s2, 0
	s_cselect_b32 s3, s3, 0
	s_add_u32 s10, s13, s2
	s_addc_u32 s11, s12, s3
	s_add_u32 s12, s9, s2
	s_mul_hi_i32 s2, s42, 0x78787879
	s_addc_u32 s13, s16, s3
	s_lshr_b32 s3, s2, 31
	s_ashr_i32 s2, s2, 3
	s_add_i32 s18, s2, s3
	s_mul_i32 s2, s18, 17
	s_lshl_b32 s16, s44, 8
	s_sub_i32 s2, s42, s2
	s_ashr_i32 s17, s16, 31
	s_cmp_lg_u32 s2, 0
	s_cselect_b32 s2, s18, 8
	s_ashr_i32 s3, s2, 31
	s_lshl_b64 s[20:21], s[2:3], 13
	s_cmp_lg_u32 s19, 32
	s_cselect_b64 s[22:23], -1, 0
	s_cmp_eq_u32 s19, 32
	s_mul_hi_i32 s9, s2, 0xc000
	s_mul_i32 s28, s2, 0xc000
	s_cselect_b64 s[2:3], -1, 0
	s_and_b64 s[24:25], s[56:57], s[2:3]
	s_add_u32 s2, s77, s20
	s_addc_u32 s3, s78, s21
	s_lshl_b64 s[20:21], s[16:17], 2
	s_add_u32 s26, s2, s20
	s_addc_u32 s27, s3, s21
	s_add_u32 s2, s71, s28
	s_addc_u32 s3, s76, s9
	s_add_u32 s28, s2, s20
	s_addc_u32 s29, s3, s21
	s_add_u32 s9, s30, 0x100
	s_addc_u32 s17, s31, 0
	s_add_u32 s2, s74, 0x80080
	s_addc_u32 s3, s75, 0
	s_mov_b32 s34, 0
	v_lshl_add_u64 v[96:97], s[2:3], 0, v[210:211]
	v_lshl_add_u64 v[98:99], s[2:3], 0, v[218:219]
	s_mov_b64 s[30:31], 0
	s_add_i32 s2, s34, 2
	s_add_u32 s3, s74, s30
	s_addc_u32 s35, s75, s31
	s_add_u32 s3, s3, 0x100
	s_addc_u32 s35, s35, 0
	s_add_u32 s39, s9, s30
	s_addc_u32 s63, s17, s31
	s_cmp_eq_u32 s45, s34
	s_cselect_b32 s89, s11, s35
	s_cselect_b32 s88, s10, s3
	s_cselect_b32 s35, s13, s63
	s_cselect_b32 s34, s12, s39
	s_add_i32 s3, 0, 0x10000
	s_add_i32 s39, 0, 0x14000
	v_add_u32_e32 v136, s3, v220
	v_add_u32_e32 v160, s39, v220
	ds_read_b128 v[108:111], v136
	ds_read_b128 v[120:123], v136 offset:1024
	ds_read_b128 v[132:135], v136 offset:2048
	ds_read_b128 v[136:139], v136 offset:3072
	ds_read_b128 v[140:143], v160
	ds_read_b128 v[144:147], v160 offset:1024
	ds_read_b128 v[148:151], v160 offset:2048
	ds_read_b128 v[160:163], v160 offset:3072
	v_lshl_add_u64 v[196:197], v[96:97], 0, s[30:31]
	s_add_i32 m0, s15, 0xc000
	ds_read_b128 v[164:167], v223
	ds_read_b128 v[168:171], v223 offset:1024
	ds_read_b128 v[172:175], v223 offset:2048
	ds_read_b128 v[176:179], v223 offset:3072
	ds_read_b128 v[180:183], v223 offset:4096
	ds_read_b128 v[184:187], v223 offset:5120
	ds_read_b128 v[188:191], v223 offset:6144
	ds_read_b128 v[192:195], v223 offset:7168
	global_load_lds_dwordx4 v[196:197], off
	v_lshl_add_u64 v[196:197], v[98:99], 0, s[30:31]
	s_add_i32 m0, s15, 0xe000
	s_nop 0
	global_load_lds_dwordx4 v[196:197], off
	s_waitcnt vmcnt(8)
	s_waitcnt lgkmcnt(0)
	s_barrier
	s_setprio 1
	s_waitcnt lgkmcnt(0)
	v_mfma_f32_16x16x32_bf16 v[156:159], v[108:111], v[164:167], 0
	v_mfma_f32_16x16x32_bf16 v[156:159], v[120:123], v[168:171], v[156:159]
	v_mfma_f32_16x16x32_bf16 v[128:131], v[108:111], v[172:175], 0
	v_mfma_f32_16x16x32_bf16 v[128:131], v[120:123], v[176:179], v[128:131]
	v_mfma_f32_16x16x32_bf16 v[116:119], v[108:111], v[180:183], 0
	v_mfma_f32_16x16x32_bf16 v[116:119], v[120:123], v[184:187], v[116:119]
	v_mfma_f32_16x16x32_bf16 v[104:107], v[108:111], v[188:191], 0
	v_mfma_f32_16x16x32_bf16 v[104:107], v[120:123], v[192:195], v[104:107]
	v_mfma_f32_16x16x32_bf16 v[152:155], v[132:135], v[164:167], 0
	v_mfma_f32_16x16x32_bf16 v[152:155], v[136:139], v[168:171], v[152:155]
	v_mfma_f32_16x16x32_bf16 v[124:127], v[132:135], v[172:175], 0
	v_mfma_f32_16x16x32_bf16 v[124:127], v[136:139], v[176:179], v[124:127]
	v_mfma_f32_16x16x32_bf16 v[112:115], v[132:135], v[180:183], 0
	v_mfma_f32_16x16x32_bf16 v[112:115], v[136:139], v[184:187], v[112:115]
	v_mfma_f32_16x16x32_bf16 v[100:103], v[132:135], v[188:191], 0
	v_mfma_f32_16x16x32_bf16 v[100:103], v[136:139], v[192:195], v[100:103]
	s_setprio 0
	s_setprio 1
	v_mfma_f32_16x16x32_bf16 v[92:95], v[140:143], v[164:167], 0
	v_mfma_f32_16x16x32_bf16 v[92:95], v[144:147], v[168:171], v[92:95]
	v_mfma_f32_16x16x32_bf16 v[84:87], v[140:143], v[172:175], 0
	v_mfma_f32_16x16x32_bf16 v[84:87], v[144:147], v[176:179], v[84:87]
	v_mfma_f32_16x16x32_bf16 v[76:79], v[140:143], v[180:183], 0
	v_mfma_f32_16x16x32_bf16 v[76:79], v[144:147], v[184:187], v[76:79]
	v_mfma_f32_16x16x32_bf16 v[68:71], v[140:143], v[188:191], 0
	v_mfma_f32_16x16x32_bf16 v[68:71], v[144:147], v[192:195], v[68:71]
	v_mfma_f32_16x16x32_bf16 v[88:91], v[148:151], v[164:167], 0
	v_mfma_f32_16x16x32_bf16 v[88:91], v[160:163], v[168:171], v[88:91]
	v_mfma_f32_16x16x32_bf16 v[80:83], v[148:151], v[172:175], 0
	v_mfma_f32_16x16x32_bf16 v[80:83], v[160:163], v[176:179], v[80:83]
	v_mfma_f32_16x16x32_bf16 v[72:75], v[148:151], v[180:183], 0
	v_mfma_f32_16x16x32_bf16 v[72:75], v[160:163], v[184:187], v[72:75]
	v_mfma_f32_16x16x32_bf16 v[64:67], v[148:151], v[188:191], 0
	v_mfma_f32_16x16x32_bf16 v[64:67], v[160:163], v[192:195], v[64:67]
	s_setprio 0
	s_barrier
	s_nop 1
	s_add_i32 s3, s3, s64
	v_lshl_add_u64 v[196:197], s[34:35], 0, v[212:213]
	s_mov_b32 m0, s3
	ds_read_b128 v[164:167], v223 offset:16384
	ds_read_b128 v[168:171], v223 offset:17408
	ds_read_b128 v[172:175], v223 offset:18432
	ds_read_b128 v[176:179], v223 offset:19456
	ds_read_b128 v[180:183], v223 offset:20480
	ds_read_b128 v[184:187], v223 offset:21504
	ds_read_b128 v[188:191], v223 offset:22528
	ds_read_b128 v[192:195], v223 offset:23552
	global_load_lds_dwordx4 v[196:197], off
	s_add_i32 m0, s3, 0x2000
	s_add_u32 vcc_lo, s34, 0x80000
	v_lshl_add_u64 v[198:199], s[34:35], 0, v[208:209]
	s_addc_u32 vcc_hi, s35, 0
	s_add_i32 s3, s39, s64
	global_load_lds_dwordx4 v[198:199], off
	v_lshl_add_u64 v[200:201], vcc, 0, v[212:213]
	s_mov_b32 m0, s3
	v_lshl_add_u64 v[202:203], s[88:89], 0, v[206:207]
	global_load_lds_dwordx4 v[200:201], off
	v_lshl_add_u64 v[200:201], vcc, 0, v[208:209]
	s_add_i32 m0, s3, 0x2000
	s_nop 0
	global_load_lds_dwordx4 v[200:201], off
	v_lshl_add_u64 v[200:201], s[88:89], 0, v[204:205]
	s_mov_b32 m0, s15
	s_nop 0
	global_load_lds_dwordx4 v[200:201], off
	s_mov_b32 m0, s43
	s_nop 0
	global_load_lds_dwordx4 v[202:203], off
	s_waitcnt vmcnt(8)
	s_waitcnt lgkmcnt(0)
	s_barrier
	s_setprio 1
	s_waitcnt lgkmcnt(0)
	v_mfma_f32_16x16x32_bf16 v[60:63], v[108:111], v[164:167], 0
	v_mfma_f32_16x16x32_bf16 v[60:63], v[120:123], v[168:171], v[60:63]
	v_mfma_f32_16x16x32_bf16 v[52:55], v[108:111], v[172:175], 0
	v_mfma_f32_16x16x32_bf16 v[52:55], v[120:123], v[176:179], v[52:55]
	v_mfma_f32_16x16x32_bf16 v[44:47], v[108:111], v[180:183], 0
	v_mfma_f32_16x16x32_bf16 v[44:47], v[120:123], v[184:187], v[44:47]
	v_mfma_f32_16x16x32_bf16 v[36:39], v[108:111], v[188:191], 0
	v_mfma_f32_16x16x32_bf16 v[36:39], v[120:123], v[192:195], v[36:39]
	v_mfma_f32_16x16x32_bf16 v[56:59], v[132:135], v[164:167], 0
	v_mfma_f32_16x16x32_bf16 v[56:59], v[136:139], v[168:171], v[56:59]
	v_mfma_f32_16x16x32_bf16 v[48:51], v[132:135], v[172:175], 0
	v_mfma_f32_16x16x32_bf16 v[48:51], v[136:139], v[176:179], v[48:51]
	v_mfma_f32_16x16x32_bf16 v[40:43], v[132:135], v[180:183], 0
	v_mfma_f32_16x16x32_bf16 v[40:43], v[136:139], v[184:187], v[40:43]
	v_mfma_f32_16x16x32_bf16 v[32:35], v[132:135], v[188:191], 0
	v_mfma_f32_16x16x32_bf16 v[32:35], v[136:139], v[192:195], v[32:35]
	s_setprio 0
	s_setprio 1
	v_mfma_f32_16x16x32_bf16 v[28:31], v[140:143], v[164:167], 0
	v_mfma_f32_16x16x32_bf16 v[28:31], v[144:147], v[168:171], v[28:31]
	v_mfma_f32_16x16x32_bf16 v[20:23], v[140:143], v[172:175], 0
	v_mfma_f32_16x16x32_bf16 v[20:23], v[144:147], v[176:179], v[20:23]
	v_mfma_f32_16x16x32_bf16 v[12:15], v[140:143], v[180:183], 0
	v_mfma_f32_16x16x32_bf16 v[12:15], v[144:147], v[184:187], v[12:15]
	v_mfma_f32_16x16x32_bf16 v[4:7], v[140:143], v[188:191], 0
	v_mfma_f32_16x16x32_bf16 v[4:7], v[144:147], v[192:195], v[4:7]
	v_mfma_f32_16x16x32_bf16 v[24:27], v[148:151], v[164:167], 0
	v_mfma_f32_16x16x32_bf16 v[24:27], v[160:163], v[168:171], v[24:27]
	v_mfma_f32_16x16x32_bf16 v[16:19], v[148:151], v[172:175], 0
	v_mfma_f32_16x16x32_bf16 v[16:19], v[160:163], v[176:179], v[16:19]
	v_mfma_f32_16x16x32_bf16 v[8:11], v[148:151], v[180:183], 0
	v_mfma_f32_16x16x32_bf16 v[8:11], v[160:163], v[184:187], v[8:11]
	v_mfma_f32_16x16x32_bf16 v[0:3], v[148:151], v[188:191], 0
	v_mfma_f32_16x16x32_bf16 v[0:3], v[160:163], v[192:195], v[0:3]
	s_setprio 0
	s_barrier
	s_nop 1
	s_add_i32 s3, 0, 0x18000
	s_add_i32 s39, 0, 0x1c000
	v_add_u32_e32 v136, s3, v220
	v_add_u32_e32 v160, s39, v220
	ds_read_b128 v[108:111], v136
	ds_read_b128 v[120:123], v136 offset:1024
	ds_read_b128 v[132:135], v136 offset:2048
	ds_read_b128 v[136:139], v136 offset:3072
	ds_read_b128 v[140:143], v160
	ds_read_b128 v[144:147], v160 offset:1024
	ds_read_b128 v[148:151], v160 offset:2048
	ds_read_b128 v[160:163], v160 offset:3072
	s_add_u32 s88, s88, 0x80000
	s_addc_u32 s89, s89, 0
	s_mov_b32 m0, s69
	v_lshl_add_u64 v[214:215], s[88:89], 0, v[204:205]
	ds_read_b128 v[164:167], v223 offset:32768
	ds_read_b128 v[168:171], v223 offset:33792
	ds_read_b128 v[172:175], v223 offset:34816
	ds_read_b128 v[176:179], v223 offset:35840
	ds_read_b128 v[180:183], v223 offset:36864
	ds_read_b128 v[184:187], v223 offset:37888
	ds_read_b128 v[188:191], v223 offset:38912
	ds_read_b128 v[192:195], v223 offset:39936
	global_load_lds_dwordx4 v[214:215], off
	v_lshl_add_u64 v[214:215], s[88:89], 0, v[206:207]
	s_mov_b32 m0, s70
	s_nop 0
	global_load_lds_dwordx4 v[214:215], off
	s_waitcnt vmcnt(8)
	s_waitcnt lgkmcnt(0)
	s_barrier
	s_setprio 1
	s_waitcnt lgkmcnt(0)
	v_mfma_f32_16x16x32_bf16 v[156:159], v[108:111], v[164:167], v[156:159]
	v_mfma_f32_16x16x32_bf16 v[156:159], v[120:123], v[168:171], v[156:159]
	v_mfma_f32_16x16x32_bf16 v[128:131], v[108:111], v[172:175], v[128:131]
	v_mfma_f32_16x16x32_bf16 v[128:131], v[120:123], v[176:179], v[128:131]
	v_mfma_f32_16x16x32_bf16 v[116:119], v[108:111], v[180:183], v[116:119]
	v_mfma_f32_16x16x32_bf16 v[116:119], v[120:123], v[184:187], v[116:119]
	v_mfma_f32_16x16x32_bf16 v[104:107], v[108:111], v[188:191], v[104:107]
	v_mfma_f32_16x16x32_bf16 v[104:107], v[120:123], v[192:195], v[104:107]
	v_mfma_f32_16x16x32_bf16 v[152:155], v[132:135], v[164:167], v[152:155]
	v_mfma_f32_16x16x32_bf16 v[152:155], v[136:139], v[168:171], v[152:155]
	v_mfma_f32_16x16x32_bf16 v[124:127], v[132:135], v[172:175], v[124:127]
	v_mfma_f32_16x16x32_bf16 v[124:127], v[136:139], v[176:179], v[124:127]
	v_mfma_f32_16x16x32_bf16 v[112:115], v[132:135], v[180:183], v[112:115]
	v_mfma_f32_16x16x32_bf16 v[112:115], v[136:139], v[184:187], v[112:115]
	v_mfma_f32_16x16x32_bf16 v[100:103], v[132:135], v[188:191], v[100:103]
	v_mfma_f32_16x16x32_bf16 v[100:103], v[136:139], v[192:195], v[100:103]
	s_setprio 0
	s_setprio 1
	v_mfma_f32_16x16x32_bf16 v[92:95], v[140:143], v[164:167], v[92:95]
	v_mfma_f32_16x16x32_bf16 v[92:95], v[144:147], v[168:171], v[92:95]
	v_mfma_f32_16x16x32_bf16 v[84:87], v[140:143], v[172:175], v[84:87]
	v_mfma_f32_16x16x32_bf16 v[84:87], v[144:147], v[176:179], v[84:87]
	v_mfma_f32_16x16x32_bf16 v[76:79], v[140:143], v[180:183], v[76:79]
	v_mfma_f32_16x16x32_bf16 v[76:79], v[144:147], v[184:187], v[76:79]
	v_mfma_f32_16x16x32_bf16 v[68:71], v[140:143], v[188:191], v[68:71]
	v_mfma_f32_16x16x32_bf16 v[68:71], v[144:147], v[192:195], v[68:71]
	v_mfma_f32_16x16x32_bf16 v[88:91], v[148:151], v[164:167], v[88:91]
	v_mfma_f32_16x16x32_bf16 v[88:91], v[160:163], v[168:171], v[88:91]
	v_mfma_f32_16x16x32_bf16 v[80:83], v[148:151], v[172:175], v[80:83]
	v_mfma_f32_16x16x32_bf16 v[80:83], v[160:163], v[176:179], v[80:83]
	v_mfma_f32_16x16x32_bf16 v[72:75], v[148:151], v[180:183], v[72:75]
	v_mfma_f32_16x16x32_bf16 v[72:75], v[160:163], v[184:187], v[72:75]
	v_mfma_f32_16x16x32_bf16 v[64:67], v[148:151], v[188:191], v[64:67]
	v_mfma_f32_16x16x32_bf16 v[64:67], v[160:163], v[192:195], v[64:67]
	s_setprio 0
	s_barrier
	s_nop 1
	s_add_i32 s3, s3, s64
	v_lshl_add_u64 v[196:197], v[196:197], 0, s[72:73]
	s_mov_b32 m0, s3
	ds_read_b128 v[164:167], v223 offset:49152
	ds_read_b128 v[168:171], v223 offset:50176
	ds_read_b128 v[172:175], v223 offset:51200
	ds_read_b128 v[176:179], v223 offset:52224
	ds_read_b128 v[180:183], v223 offset:53248
	ds_read_b128 v[184:187], v223 offset:54272
	ds_read_b128 v[188:191], v223 offset:55296
	ds_read_b128 v[192:195], v223 offset:56320
	global_load_lds_dwordx4 v[196:197], off
	s_add_i32 m0, s3, 0x2000
	s_add_u32 s34, s34, 0x80080
	v_lshl_add_u64 v[196:197], v[198:199], 0, s[72:73]
	s_addc_u32 s35, s35, 0
	s_add_i32 s3, s39, s64
	global_load_lds_dwordx4 v[196:197], off
	v_lshl_add_u64 v[196:197], s[34:35], 0, v[212:213]
	s_mov_b32 m0, s3
	s_nop 0
	global_load_lds_dwordx4 v[196:197], off
	v_lshl_add_u64 v[196:197], s[34:35], 0, v[208:209]
	s_add_i32 m0, s3, 0x2000
	s_nop 0
	global_load_lds_dwordx4 v[196:197], off
	v_lshl_add_u64 v[196:197], v[200:201], 0, s[72:73]
	s_mov_b32 m0, s83
	s_nop 0
	global_load_lds_dwordx4 v[196:197], off
	v_lshl_add_u64 v[196:197], v[202:203], 0, s[72:73]
	s_mov_b32 m0, s84
	s_nop 0
	global_load_lds_dwordx4 v[196:197], off
	s_waitcnt vmcnt(8)
	s_waitcnt lgkmcnt(0)
	s_barrier
	s_setprio 1
	s_waitcnt lgkmcnt(0)
	v_mfma_f32_16x16x32_bf16 v[60:63], v[108:111], v[164:167], v[60:63]
	v_mfma_f32_16x16x32_bf16 v[60:63], v[120:123], v[168:171], v[60:63]
	v_mfma_f32_16x16x32_bf16 v[52:55], v[108:111], v[172:175], v[52:55]
	v_mfma_f32_16x16x32_bf16 v[52:55], v[120:123], v[176:179], v[52:55]
	v_mfma_f32_16x16x32_bf16 v[44:47], v[108:111], v[180:183], v[44:47]
	v_mfma_f32_16x16x32_bf16 v[44:47], v[120:123], v[184:187], v[44:47]
	v_mfma_f32_16x16x32_bf16 v[36:39], v[108:111], v[188:191], v[36:39]
	v_mfma_f32_16x16x32_bf16 v[36:39], v[120:123], v[192:195], v[36:39]
	v_mfma_f32_16x16x32_bf16 v[56:59], v[132:135], v[164:167], v[56:59]
	v_mfma_f32_16x16x32_bf16 v[56:59], v[136:139], v[168:171], v[56:59]
	v_mfma_f32_16x16x32_bf16 v[48:51], v[132:135], v[172:175], v[48:51]
	v_mfma_f32_16x16x32_bf16 v[48:51], v[136:139], v[176:179], v[48:51]
	v_mfma_f32_16x16x32_bf16 v[40:43], v[132:135], v[180:183], v[40:43]
	v_mfma_f32_16x16x32_bf16 v[40:43], v[136:139], v[184:187], v[40:43]
	v_mfma_f32_16x16x32_bf16 v[32:35], v[132:135], v[188:191], v[32:35]
	v_mfma_f32_16x16x32_bf16 v[32:35], v[136:139], v[192:195], v[32:35]
	s_setprio 0
	s_setprio 1
	v_mfma_f32_16x16x32_bf16 v[28:31], v[140:143], v[164:167], v[28:31]
	v_mfma_f32_16x16x32_bf16 v[28:31], v[144:147], v[168:171], v[28:31]
	v_mfma_f32_16x16x32_bf16 v[20:23], v[140:143], v[172:175], v[20:23]
	v_mfma_f32_16x16x32_bf16 v[20:23], v[144:147], v[176:179], v[20:23]
	v_mfma_f32_16x16x32_bf16 v[12:15], v[140:143], v[180:183], v[12:15]
	v_mfma_f32_16x16x32_bf16 v[12:15], v[144:147], v[184:187], v[12:15]
	v_mfma_f32_16x16x32_bf16 v[4:7], v[140:143], v[188:191], v[4:7]
	v_mfma_f32_16x16x32_bf16 v[4:7], v[144:147], v[192:195], v[4:7]
	v_mfma_f32_16x16x32_bf16 v[24:27], v[148:151], v[164:167], v[24:27]
	v_mfma_f32_16x16x32_bf16 v[24:27], v[160:163], v[168:171], v[24:27]
	v_mfma_f32_16x16x32_bf16 v[16:19], v[148:151], v[172:175], v[16:19]
	v_mfma_f32_16x16x32_bf16 v[16:19], v[160:163], v[176:179], v[16:19]
	v_mfma_f32_16x16x32_bf16 v[8:11], v[148:151], v[180:183], v[8:11]
	v_mfma_f32_16x16x32_bf16 v[8:11], v[160:163], v[184:187], v[8:11]
	v_mfma_f32_16x16x32_bf16 v[0:3], v[148:151], v[188:191], v[0:3]
	v_mfma_f32_16x16x32_bf16 v[0:3], v[160:163], v[192:195], v[0:3]
	s_setprio 0
	s_barrier
	s_nop 1
	s_add_u32 s30, s30, 0x100
	s_addc_u32 s31, s31, 0
	s_cmp_ge_i32 s2, s19
	s_mov_b32 s34, s2
	s_cbranch_scc1 .LBB0_1246
	s_branch .LBB0_1240

.LBB0_1412:
	s_ashr_i32 s59, s58, 31
	s_lshl_b64 s[2:3], s[58:59], 20
	s_add_u32 s60, s31, s2
	s_addc_u32 s61, s35, s3
	s_and_b64 s[2:3], s[36:37], exec
	s_cselect_b32 s5, s61, s75
	s_cselect_b32 s59, s60, s74
	s_ashr_i32 s57, s56, 31
	s_lshl_b64 s[2:3], s[56:57], 20
	s_add_u32 s62, s49, s2
	s_addc_u32 s63, s66, s3
	s_and_b64 s[2:3], s[36:37], exec
	s_cselect_b32 s57, s63, s15
	s_cselect_b32 s30, s62, s14
	s_lshl_b32 s8, s10, 8
	s_ashr_i32 s9, s8, 31
	s_lshl_b64 s[2:3], s[8:9], 5
	s_mul_hi_i32 s9, s10, 0x78787879
	s_lshr_b32 s13, s9, 31
	s_ashr_i32 s9, s9, 3
	s_add_i32 s9, s9, s13
	s_mul_i32 s13, s9, 17
	s_lshl_b32 s18, s12, 8
	s_lshl_b32 s12, s12, 7
	s_sub_i32 s16, s10, s13
	s_ashr_i32 s19, s18, 31
	s_ashr_i32 s13, s12, 31
	s_mul_i32 s17, s9, 0xf400
	s_mul_hi_i32 s20, s9, 0xf400
	s_cmp_lg_u32 s16, 0
	s_cselect_b32 s21, s20, 0
	s_cselect_b32 s20, s17, 0x7a000
	s_add_u32 s16, s91, s2
	s_addc_u32 s17, s95, s3
	s_lshl_b64 s[2:3], s[20:21], 2
	s_add_u32 s20, s97, s2
	s_addc_u32 s21, s33, s3
	s_lshl_b64 s[2:3], s[18:19], 2
	s_add_u32 s18, s20, s2
	s_mov_b32 s9, 0
	s_addc_u32 s19, s21, s3
	s_lshl_b32 s2, s9, 7
	s_add_u32 s3, s74, s2
	s_addc_u32 s24, s75, 0
	s_add_u32 s20, s3, 0x100
	s_addc_u32 s21, s24, 0
	s_add_u32 s2, s14, s2
	s_addc_u32 s22, s15, 0
	s_add_u32 s2, s2, 0x100
	s_addc_u32 s25, s22, 0
	s_cmp_eq_u32 s9, 30
	s_cselect_b32 s23, s5, s21
	s_cselect_b32 s22, s59, s20
	s_cselect_b32 s21, s57, s25
	s_cselect_b32 s20, s30, s2
	s_add_i32 s25, 0, 0x10000
	s_add_i32 s26, 0, 0x14000
	v_add_u32_e32 v28, s25, v226
	v_add_u32_e32 v44, s26, v226
	ds_read_b128 v[16:19], v28
	ds_read_b128 v[20:23], v28 offset:1024
	ds_read_b128 v[24:27], v28 offset:2048
	ds_read_b128 v[28:31], v28 offset:3072
	ds_read_b128 v[32:35], v44
	ds_read_b128 v[36:39], v44 offset:1024
	ds_read_b128 v[40:43], v44 offset:2048
	ds_read_b128 v[44:47], v44 offset:3072
	s_add_u32 s2, s3, 0x80080
	s_addc_u32 s3, s24, 0
	v_lshl_add_u64 v[152:153], s[2:3], 0, v[218:219]
	s_add_i32 m0, s11, 0xc000
	ds_read_b128 v[48:51], v227
	ds_read_b128 v[52:55], v227 offset:1024
	ds_read_b128 v[56:59], v227 offset:2048
	ds_read_b128 v[60:63], v227 offset:3072
	ds_read_b128 v[136:139], v227 offset:4096
	ds_read_b128 v[140:143], v227 offset:5120
	ds_read_b128 v[144:147], v227 offset:6144
	ds_read_b128 v[148:151], v227 offset:7168
	global_load_lds_dwordx4 v[152:153], off
	v_lshl_add_u64 v[152:153], s[2:3], 0, v[222:223]
	s_add_i32 m0, s11, 0xe000
	s_nop 0
	global_load_lds_dwordx4 v[152:153], off
	s_waitcnt vmcnt(8)
	s_waitcnt lgkmcnt(0)
	s_barrier
	s_setprio 1
	s_waitcnt lgkmcnt(0)
	v_mfma_f32_16x16x32_bf16 v[152:155], v[16:19], v[48:51], 0
	v_mfma_f32_16x16x32_bf16 v[152:155], v[20:23], v[52:55], v[152:155]
	v_mfma_f32_16x16x32_bf16 v[160:163], v[16:19], v[56:59], 0
	v_mfma_f32_16x16x32_bf16 v[160:163], v[20:23], v[60:63], v[160:163]
	v_mfma_f32_16x16x32_bf16 v[108:111], v[16:19], v[136:139], 0
	v_mfma_f32_16x16x32_bf16 v[108:111], v[20:23], v[140:143], v[108:111]
	v_mfma_f32_16x16x32_bf16 v[164:167], v[16:19], v[144:147], 0
	v_mfma_f32_16x16x32_bf16 v[168:171], v[20:23], v[148:151], v[164:167]
	v_mfma_f32_16x16x32_bf16 v[64:67], v[24:27], v[48:51], 0
	v_mfma_f32_16x16x32_bf16 v[64:67], v[28:31], v[52:55], v[64:67]
	v_mfma_f32_16x16x32_bf16 v[156:159], v[24:27], v[56:59], 0
	v_mfma_f32_16x16x32_bf16 v[156:159], v[28:31], v[60:63], v[156:159]
	v_mfma_f32_16x16x32_bf16 v[104:107], v[24:27], v[136:139], 0
	v_mfma_f32_16x16x32_bf16 v[104:107], v[28:31], v[140:143], v[104:107]
	v_mfma_f32_16x16x32_bf16 v[68:71], v[24:27], v[144:147], 0
	v_mfma_f32_16x16x32_bf16 v[68:71], v[28:31], v[148:151], v[68:71]
	s_setprio 0
	s_setprio 1
	v_mfma_f32_16x16x32_bf16 v[88:91], v[32:35], v[48:51], 0
	v_mfma_f32_16x16x32_bf16 v[88:91], v[36:39], v[52:55], v[88:91]
	v_mfma_f32_16x16x32_bf16 v[48:51], v[40:43], v[48:51], 0
	v_mfma_f32_16x16x32_bf16 v[48:51], v[44:47], v[52:55], v[48:51]
	v_mfma_f32_16x16x32_bf16 v[72:75], v[40:43], v[136:139], 0
	v_mfma_f32_16x16x32_bf16 v[96:99], v[44:47], v[140:143], v[72:75]
	v_mfma_f32_16x16x32_bf16 v[72:75], v[32:35], v[144:147], 0
	v_mfma_f32_16x16x32_bf16 v[92:95], v[36:39], v[148:151], v[72:75]
	v_mfma_f32_16x16x32_bf16 v[52:55], v[32:35], v[56:59], 0
	v_mfma_f32_16x16x32_bf16 v[52:55], v[36:39], v[60:63], v[52:55]
	v_mfma_f32_16x16x32_bf16 v[56:59], v[40:43], v[56:59], 0
	v_mfma_f32_16x16x32_bf16 v[56:59], v[44:47], v[60:63], v[56:59]
	v_mfma_f32_16x16x32_bf16 v[72:75], v[40:43], v[144:147], 0
	v_mfma_f32_16x16x32_bf16 v[76:79], v[44:47], v[148:151], v[72:75]
	v_mfma_f32_16x16x32_bf16 v[60:63], v[32:35], v[136:139], 0
	v_mfma_f32_16x16x32_bf16 v[60:63], v[36:39], v[140:143], v[60:63]
	s_setprio 0
	s_barrier
	s_nop 1
	s_add_i32 s2, s25, s79
	v_lshl_add_u64 v[214:215], s[20:21], 0, v[220:221]
	s_mov_b32 m0, s2
	ds_read_b128 v[72:75], v227 offset:16384
	ds_read_b128 v[100:103], v227 offset:17408
	ds_read_b128 v[128:131], v227 offset:18432
	ds_read_b128 v[132:135], v227 offset:19456
	ds_read_b128 v[136:139], v227 offset:20480
	ds_read_b128 v[140:143], v227 offset:21504
	ds_read_b128 v[144:147], v227 offset:22528
	ds_read_b128 v[148:151], v227 offset:23552
	global_load_lds_dwordx4 v[214:215], off
	s_add_i32 m0, s2, 0x2000
	s_add_u32 s2, s20, 0x80000
	v_lshl_add_u64 v[216:217], s[20:21], 0, v[224:225]
	s_addc_u32 s3, s21, 0
	s_add_i32 s24, s26, s79
	global_load_lds_dwordx4 v[216:217], off
	v_lshl_add_u64 v[164:165], s[2:3], 0, v[220:221]
	s_mov_b32 m0, s24
	v_lshl_add_u64 v[230:231], s[22:23], 0, v[218:219]
	global_load_lds_dwordx4 v[164:165], off
	v_lshl_add_u64 v[164:165], s[2:3], 0, v[224:225]
	s_add_i32 m0, s24, 0x2000
	v_lshl_add_u64 v[232:233], s[22:23], 0, v[222:223]
	global_load_lds_dwordx4 v[164:165], off
	s_mov_b32 m0, s11
	s_nop 0
	global_load_lds_dwordx4 v[230:231], off
	s_mov_b32 m0, s88
	s_nop 0
	global_load_lds_dwordx4 v[232:233], off
	s_waitcnt vmcnt(8)
	s_waitcnt lgkmcnt(0)
	s_barrier
	s_setprio 1
	s_waitcnt lgkmcnt(0)
	v_mfma_f32_16x16x32_bf16 v[80:83], v[16:19], v[72:75], 0
	v_mfma_f32_16x16x32_bf16 v[80:83], v[20:23], v[100:103], v[80:83]
	v_mfma_f32_16x16x32_bf16 v[12:15], v[16:19], v[128:131], 0
	v_mfma_f32_16x16x32_bf16 v[12:15], v[20:23], v[132:135], v[12:15]
	v_mfma_f32_16x16x32_bf16 v[124:127], v[16:19], v[136:139], 0
	v_mfma_f32_16x16x32_bf16 v[124:127], v[20:23], v[140:143], v[124:127]
	v_mfma_f32_16x16x32_bf16 v[8:11], v[24:27], v[128:131], 0
	v_mfma_f32_16x16x32_bf16 v[8:11], v[28:31], v[132:135], v[8:11]
	v_mfma_f32_16x16x32_bf16 v[120:123], v[24:27], v[136:139], 0
	v_mfma_f32_16x16x32_bf16 v[120:123], v[28:31], v[140:143], v[120:123]
	v_mfma_f32_16x16x32_bf16 v[16:19], v[16:19], v[144:147], 0
	v_mfma_f32_16x16x32_bf16 v[16:19], v[20:23], v[148:151], v[16:19]
	v_mfma_f32_16x16x32_bf16 v[164:167], v[24:27], v[72:75], 0
	v_mfma_f32_16x16x32_bf16 v[176:179], v[28:31], v[100:103], v[164:167]
	v_mfma_f32_16x16x32_bf16 v[20:23], v[24:27], v[144:147], 0
	v_mfma_f32_16x16x32_bf16 v[20:23], v[28:31], v[148:151], v[20:23]
	s_setprio 0
	s_setprio 1
	v_mfma_f32_16x16x32_bf16 v[24:27], v[32:35], v[72:75], 0
	v_mfma_f32_16x16x32_bf16 v[24:27], v[36:39], v[100:103], v[24:27]
	v_mfma_f32_16x16x32_bf16 v[4:7], v[32:35], v[128:131], 0
	v_mfma_f32_16x16x32_bf16 v[4:7], v[36:39], v[132:135], v[4:7]
	v_mfma_f32_16x16x32_bf16 v[28:31], v[40:43], v[72:75], 0
	v_mfma_f32_16x16x32_bf16 v[28:31], v[44:47], v[100:103], v[28:31]
	v_mfma_f32_16x16x32_bf16 v[72:75], v[32:35], v[136:139], 0
	v_mfma_f32_16x16x32_bf16 v[116:119], v[36:39], v[140:143], v[72:75]
	v_mfma_f32_16x16x32_bf16 v[0:3], v[40:43], v[128:131], 0
	v_mfma_f32_16x16x32_bf16 v[0:3], v[44:47], v[132:135], v[0:3]
	v_mfma_f32_16x16x32_bf16 v[72:75], v[40:43], v[136:139], 0
	v_mfma_f32_16x16x32_bf16 v[112:115], v[44:47], v[140:143], v[72:75]
	v_mfma_f32_16x16x32_bf16 v[32:35], v[32:35], v[144:147], 0
	v_mfma_f32_16x16x32_bf16 v[32:35], v[36:39], v[148:151], v[32:35]
	v_mfma_f32_16x16x32_bf16 v[36:39], v[40:43], v[144:147], 0
	v_mfma_f32_16x16x32_bf16 v[36:39], v[44:47], v[148:151], v[36:39]
	s_setprio 0
	s_barrier
	s_nop 1
	s_add_i32 s24, 0, 0x18000
	v_add_u32_e32 v72, s24, v226
	s_add_i32 s25, 0, 0x1c000
	ds_read_b128 v[40:43], v72
	ds_read_b128 v[44:47], v72 offset:1024
	ds_read_b128 v[136:139], v72 offset:2048
	ds_read_b128 v[140:143], v72 offset:3072
	v_add_u32_e32 v72, s25, v226
	ds_read_b128 v[144:147], v72
	ds_read_b128 v[148:151], v72 offset:1024
	ds_read_b128 v[184:187], v72 offset:2048
	ds_read_b128 v[192:195], v72 offset:3072
	s_add_u32 s2, s22, 0x80000
	s_addc_u32 s3, s23, 0
	s_mov_b32 m0, s89
	v_lshl_add_u64 v[132:133], s[2:3], 0, v[218:219]
	ds_read_b128 v[72:75], v227 offset:32768
	ds_read_b128 v[84:87], v227 offset:33792
	ds_read_b128 v[100:103], v227 offset:34816
	ds_read_b128 v[128:131], v227 offset:35840
	ds_read_b128 v[172:175], v227 offset:36864
	ds_read_b128 v[180:183], v227 offset:37888
	ds_read_b128 v[188:191], v227 offset:38912
	ds_read_b128 v[196:199], v227 offset:39936
	global_load_lds_dwordx4 v[132:133], off
	v_lshl_add_u64 v[132:133], s[2:3], 0, v[222:223]
	s_mov_b32 m0, s76
	s_nop 0
	global_load_lds_dwordx4 v[132:133], off
	s_waitcnt vmcnt(8)
	s_waitcnt lgkmcnt(0)
	s_barrier
	s_setprio 1
	s_waitcnt lgkmcnt(0)
	v_mfma_f32_16x16x32_bf16 v[132:135], v[40:43], v[72:75], v[152:155]
	v_mfma_f32_16x16x32_bf16 v[164:167], v[44:47], v[84:87], v[132:135]
	v_mfma_f32_16x16x32_bf16 v[108:111], v[40:43], v[172:175], v[108:111]
	v_mfma_f32_16x16x32_bf16 v[108:111], v[44:47], v[180:183], v[108:111]
	v_mfma_f32_16x16x32_bf16 v[132:135], v[40:43], v[100:103], v[160:163]
	v_mfma_f32_16x16x32_bf16 v[160:163], v[44:47], v[128:131], v[132:135]
	v_mfma_f32_16x16x32_bf16 v[132:135], v[136:139], v[100:103], v[156:159]
	v_mfma_f32_16x16x32_bf16 v[156:159], v[140:143], v[128:131], v[132:135]
	v_mfma_f32_16x16x32_bf16 v[132:135], v[40:43], v[188:191], v[168:171]
	v_mfma_f32_16x16x32_bf16 v[168:171], v[44:47], v[196:199], v[132:135]
	v_mfma_f32_16x16x32_bf16 v[64:67], v[136:139], v[72:75], v[64:67]
	v_mfma_f32_16x16x32_bf16 v[64:67], v[140:143], v[84:87], v[64:67]
	v_mfma_f32_16x16x32_bf16 v[104:107], v[136:139], v[172:175], v[104:107]
	v_mfma_f32_16x16x32_bf16 v[104:107], v[140:143], v[180:183], v[104:107]
	v_mfma_f32_16x16x32_bf16 v[68:71], v[136:139], v[188:191], v[68:71]
	v_mfma_f32_16x16x32_bf16 v[68:71], v[140:143], v[196:199], v[68:71]
	s_setprio 0
	s_setprio 1
	v_mfma_f32_16x16x32_bf16 v[48:51], v[184:187], v[72:75], v[48:51]
	v_mfma_f32_16x16x32_bf16 v[88:91], v[144:147], v[72:75], v[88:91]
	v_mfma_f32_16x16x32_bf16 v[88:91], v[148:151], v[84:87], v[88:91]
	v_mfma_f32_16x16x32_bf16 v[72:75], v[192:195], v[84:87], v[48:51]
	v_mfma_f32_16x16x32_bf16 v[48:51], v[144:147], v[100:103], v[52:55]
	v_mfma_f32_16x16x32_bf16 v[132:135], v[148:151], v[128:131], v[48:51]
	v_mfma_f32_16x16x32_bf16 v[48:51], v[184:187], v[100:103], v[56:59]
	v_mfma_f32_16x16x32_bf16 v[128:131], v[192:195], v[128:131], v[48:51]
	v_mfma_f32_16x16x32_bf16 v[48:51], v[144:147], v[172:175], v[60:63]
	v_mfma_f32_16x16x32_bf16 v[100:103], v[148:151], v[180:183], v[48:51]
	v_mfma_f32_16x16x32_bf16 v[48:51], v[184:187], v[172:175], v[96:99]
	v_mfma_f32_16x16x32_bf16 v[96:99], v[192:195], v[180:183], v[48:51]
	v_mfma_f32_16x16x32_bf16 v[48:51], v[144:147], v[188:191], v[92:95]
	v_mfma_f32_16x16x32_bf16 v[92:95], v[148:151], v[196:199], v[48:51]
	v_mfma_f32_16x16x32_bf16 v[48:51], v[184:187], v[188:191], v[76:79]
	v_mfma_f32_16x16x32_bf16 v[76:79], v[192:195], v[196:199], v[48:51]
	s_setprio 0
	s_barrier
	s_nop 1
	s_add_i32 s2, s24, s79
	v_lshl_add_u64 v[84:85], v[214:215], 0, s[72:73]
	s_mov_b32 m0, s2
	s_nop 0
	ds_read_b128 v[48:51], v227 offset:49152
	ds_read_b128 v[52:55], v227 offset:50176
	ds_read_b128 v[56:59], v227 offset:51200
	ds_read_b128 v[60:63], v227 offset:52224
	ds_read_b128 v[152:155], v227 offset:53248
	ds_read_b128 v[180:183], v227 offset:54272
	ds_read_b128 v[204:207], v227 offset:55296
	ds_read_b128 v[208:211], v227 offset:56320
	global_load_lds_dwordx4 v[84:85], off
	s_add_i32 m0, s2, 0x2000
	s_add_u32 s2, s20, 0x80080
	v_lshl_add_u64 v[84:85], v[216:217], 0, s[72:73]
	s_addc_u32 s3, s21, 0
	s_add_i32 s20, s25, s79
	global_load_lds_dwordx4 v[84:85], off
	v_lshl_add_u64 v[84:85], s[2:3], 0, v[220:221]
	s_mov_b32 m0, s20
	s_nop 0
	global_load_lds_dwordx4 v[84:85], off
	v_lshl_add_u64 v[84:85], s[2:3], 0, v[224:225]
	s_add_i32 m0, s20, 0x2000
	s_nop 0
	global_load_lds_dwordx4 v[84:85], off
	v_lshl_add_u64 v[84:85], v[230:231], 0, s[72:73]
	s_mov_b32 m0, s67
	s_nop 0
	global_load_lds_dwordx4 v[84:85], off
	v_lshl_add_u64 v[84:85], v[232:233], 0, s[72:73]
	s_mov_b32 m0, s84
	s_nop 0
	global_load_lds_dwordx4 v[84:85], off
	s_waitcnt vmcnt(8)
	s_waitcnt lgkmcnt(0)
	s_barrier
	s_setprio 1
	s_waitcnt lgkmcnt(0)
	v_mfma_f32_16x16x32_bf16 v[84:87], v[136:139], v[48:51], v[176:179]
	v_mfma_f32_16x16x32_bf16 v[196:199], v[140:143], v[52:55], v[84:87]
	v_mfma_f32_16x16x32_bf16 v[12:15], v[40:43], v[56:59], v[12:15]
	v_mfma_f32_16x16x32_bf16 v[12:15], v[44:47], v[60:63], v[12:15]
	v_mfma_f32_16x16x32_bf16 v[84:87], v[40:43], v[152:155], v[124:127]
	v_mfma_f32_16x16x32_bf16 v[124:127], v[44:47], v[180:183], v[84:87]
	v_mfma_f32_16x16x32_bf16 v[84:87], v[136:139], v[152:155], v[120:123]
	v_mfma_f32_16x16x32_bf16 v[120:123], v[140:143], v[180:183], v[84:87]
	v_mfma_f32_16x16x32_bf16 v[16:19], v[40:43], v[204:207], v[16:19]
	v_mfma_f32_16x16x32_bf16 v[84:87], v[44:47], v[208:211], v[16:19]
	v_mfma_f32_16x16x32_bf16 v[80:83], v[40:43], v[48:51], v[80:83]
	v_mfma_f32_16x16x32_bf16 v[80:83], v[44:47], v[52:55], v[80:83]
	v_mfma_f32_16x16x32_bf16 v[8:11], v[136:139], v[56:59], v[8:11]
	v_mfma_f32_16x16x32_bf16 v[8:11], v[140:143], v[60:63], v[8:11]
	v_mfma_f32_16x16x32_bf16 v[16:19], v[136:139], v[204:207], v[20:23]
	v_mfma_f32_16x16x32_bf16 v[200:203], v[140:143], v[208:211], v[16:19]
	s_setprio 0
	s_setprio 1
	v_mfma_f32_16x16x32_bf16 v[4:7], v[144:147], v[56:59], v[4:7]
	v_mfma_f32_16x16x32_bf16 v[4:7], v[148:151], v[60:63], v[4:7]
	v_mfma_f32_16x16x32_bf16 v[16:19], v[144:147], v[48:51], v[24:27]
	v_mfma_f32_16x16x32_bf16 v[172:175], v[148:151], v[52:55], v[16:19]
	v_mfma_f32_16x16x32_bf16 v[16:19], v[184:187], v[48:51], v[28:31]
	v_mfma_f32_16x16x32_bf16 v[188:191], v[192:195], v[52:55], v[16:19]
	v_mfma_f32_16x16x32_bf16 v[16:19], v[144:147], v[152:155], v[116:119]
	v_mfma_f32_16x16x32_bf16 v[116:119], v[148:151], v[180:183], v[16:19]
	v_mfma_f32_16x16x32_bf16 v[16:19], v[184:187], v[152:155], v[112:115]
	v_mfma_f32_16x16x32_bf16 v[112:115], v[192:195], v[180:183], v[16:19]
	v_mfma_f32_16x16x32_bf16 v[16:19], v[144:147], v[204:207], v[32:35]
	v_mfma_f32_16x16x32_bf16 v[180:183], v[148:151], v[208:211], v[16:19]
	v_mfma_f32_16x16x32_bf16 v[0:3], v[184:187], v[56:59], v[0:3]
	v_mfma_f32_16x16x32_bf16 v[0:3], v[192:195], v[60:63], v[0:3]
	v_mfma_f32_16x16x32_bf16 v[16:19], v[184:187], v[204:207], v[36:39]
	v_mfma_f32_16x16x32_bf16 v[192:195], v[192:195], v[208:211], v[16:19]
	s_setprio 0
	s_barrier
	s_nop 1
	s_add_i32 s2, s9, 2
	s_cmp_gt_u32 s9, 29
	s_mov_b32 s9, s2
	s_cbranch_scc1 .LBB0_1436
	s_branch .LBB0_1414

.LBB0_1659:
	s_ashr_i32 s63, s62, 31
	s_add_i32 s40, s17, -2
	s_lshl_b64 s[14:15], s[62:63], 7
	s_and_b64 s[18:19], s[38:39], exec
	s_cselect_b32 s14, s14, 0
	s_cselect_b32 s15, s15, 0
	s_add_u32 s74, s2, s14
	s_addc_u32 s75, s3, s15
	s_add_u32 s8, s8, s14
	s_mul_hi_i32 s2, s43, 0x78787879
	s_addc_u32 s9, s9, s15
	s_lshr_b32 s3, s2, 31
	s_ashr_i32 s2, s2, 3
	s_add_i32 s16, s2, s3
	s_mul_i32 s2, s16, 17
	s_lshl_b32 s14, s42, 8
	s_sub_i32 s2, s43, s2
	s_ashr_i32 s15, s14, 31
	s_cmp_lg_u32 s2, 0
	s_cselect_b32 s2, s16, 8
	s_ashr_i32 s3, s2, 31
	s_lshl_b64 s[18:19], s[2:3], 13
	s_cmpk_lg_i32 s17, 0x58
	s_cselect_b64 s[20:21], -1, 0
	s_cmpk_eq_i32 s17, 0x58
	s_mul_hi_i32 s29, s2, 0xc000
	s_mul_i32 s30, s2, 0xc000
	s_cselect_b64 s[2:3], -1, 0
	s_and_b64 s[22:23], s[56:57], s[2:3]
	s_add_u32 s2, s70, s18
	s_addc_u32 s3, s71, s19
	s_lshl_b64 s[18:19], s[14:15], 2
	s_add_u32 s24, s2, s18
	s_addc_u32 s25, s3, s19
	s_add_u32 s2, s64, s30
	s_addc_u32 s3, s68, s29
	s_add_u32 s38, s2, s18
	s_addc_u32 s39, s3, s19
	s_add_u32 s15, s26, 0x100
	s_addc_u32 s41, s27, 0
	s_add_u32 s2, s12, 0x160080
	s_addc_u32 s3, s13, 0
	s_mov_b32 s28, 0
	v_lshl_add_u64 v[68:69], s[2:3], 0, v[222:223]
	v_lshl_add_u64 v[70:71], s[2:3], 0, v[224:225]
	s_mov_b64 s[26:27], 0
	s_waitcnt lgkmcnt(0)
	s_add_i32 s2, s28, 2
	s_add_u32 s3, s12, s26
	s_addc_u32 s29, s13, s27
	s_add_u32 s3, s3, 0x100
	s_addc_u32 s29, s29, 0
	s_add_u32 s55, s15, s26
	s_addc_u32 s63, s41, s27
	s_cmp_eq_u32 s40, s28
	s_cselect_b32 s31, s75, s29
	s_cselect_b32 s30, s74, s3
	s_cselect_b32 s29, s9, s63
	s_cselect_b32 s28, s8, s55
	s_add_i32 s3, 0, 0x10000
	s_add_i32 s55, 0, 0x14000
	v_add_u32_e32 v112, s3, v238
	v_add_u32_e32 v160, s55, v238
	ds_read_b128 v[76:79], v112
	ds_read_b128 v[88:91], v112 offset:1024
	ds_read_b128 v[100:103], v112 offset:2048
	ds_read_b128 v[112:115], v112 offset:3072
	ds_read_b128 v[124:127], v160
	ds_read_b128 v[136:139], v160 offset:1024
	ds_read_b128 v[148:151], v160 offset:2048
	ds_read_b128 v[160:163], v160 offset:3072
	v_lshl_add_u64 v[196:197], v[68:69], 0, s[26:27]
	s_add_i32 m0, s11, 0xc000
	ds_read_b128 v[164:167], v241
	ds_read_b128 v[168:171], v241 offset:1024
	ds_read_b128 v[172:175], v241 offset:2048
	ds_read_b128 v[176:179], v241 offset:3072
	ds_read_b128 v[180:183], v241 offset:4096
	ds_read_b128 v[184:187], v241 offset:5120
	ds_read_b128 v[188:191], v241 offset:6144
	ds_read_b128 v[192:195], v241 offset:7168
	global_load_lds_dwordx4 v[196:197], off
	v_lshl_add_u64 v[196:197], v[70:71], 0, s[26:27]
	s_add_i32 m0, s11, 0xe000
	s_nop 0
	global_load_lds_dwordx4 v[196:197], off
	s_waitcnt vmcnt(8)
	s_waitcnt lgkmcnt(0)
	s_barrier
	s_setprio 1
	s_waitcnt lgkmcnt(0)
	v_mfma_f32_16x16x32_bf16 v[156:159], v[76:79], v[164:167], 0
	v_mfma_f32_16x16x32_bf16 v[156:159], v[88:91], v[168:171], v[156:159]
	v_mfma_f32_16x16x32_bf16 v[144:147], v[76:79], v[172:175], 0
	v_mfma_f32_16x16x32_bf16 v[144:147], v[88:91], v[176:179], v[144:147]
	v_mfma_f32_16x16x32_bf16 v[132:135], v[76:79], v[180:183], 0
	v_mfma_f32_16x16x32_bf16 v[132:135], v[88:91], v[184:187], v[132:135]
	v_mfma_f32_16x16x32_bf16 v[120:123], v[76:79], v[188:191], 0
	v_mfma_f32_16x16x32_bf16 v[120:123], v[88:91], v[192:195], v[120:123]
	v_mfma_f32_16x16x32_bf16 v[152:155], v[100:103], v[164:167], 0
	v_mfma_f32_16x16x32_bf16 v[152:155], v[112:115], v[168:171], v[152:155]
	v_mfma_f32_16x16x32_bf16 v[140:143], v[100:103], v[172:175], 0
	v_mfma_f32_16x16x32_bf16 v[140:143], v[112:115], v[176:179], v[140:143]
	v_mfma_f32_16x16x32_bf16 v[128:131], v[100:103], v[180:183], 0
	v_mfma_f32_16x16x32_bf16 v[128:131], v[112:115], v[184:187], v[128:131]
	v_mfma_f32_16x16x32_bf16 v[116:119], v[100:103], v[188:191], 0
	v_mfma_f32_16x16x32_bf16 v[116:119], v[112:115], v[192:195], v[116:119]
	s_setprio 0
	s_setprio 1
	v_mfma_f32_16x16x32_bf16 v[108:111], v[124:127], v[164:167], 0
	v_mfma_f32_16x16x32_bf16 v[108:111], v[136:139], v[168:171], v[108:111]
	v_mfma_f32_16x16x32_bf16 v[96:99], v[124:127], v[172:175], 0
	v_mfma_f32_16x16x32_bf16 v[96:99], v[136:139], v[176:179], v[96:99]
	v_mfma_f32_16x16x32_bf16 v[84:87], v[124:127], v[180:183], 0
	v_mfma_f32_16x16x32_bf16 v[84:87], v[136:139], v[184:187], v[84:87]
	v_mfma_f32_16x16x32_bf16 v[72:75], v[124:127], v[188:191], 0
	v_mfma_f32_16x16x32_bf16 v[72:75], v[136:139], v[192:195], v[72:75]
	v_mfma_f32_16x16x32_bf16 v[104:107], v[148:151], v[164:167], 0
	v_mfma_f32_16x16x32_bf16 v[104:107], v[160:163], v[168:171], v[104:107]
	v_mfma_f32_16x16x32_bf16 v[92:95], v[148:151], v[172:175], 0
	v_mfma_f32_16x16x32_bf16 v[92:95], v[160:163], v[176:179], v[92:95]
	v_mfma_f32_16x16x32_bf16 v[80:83], v[148:151], v[180:183], 0
	v_mfma_f32_16x16x32_bf16 v[80:83], v[160:163], v[184:187], v[80:83]
	v_mfma_f32_16x16x32_bf16 v[64:67], v[148:151], v[188:191], 0
	v_mfma_f32_16x16x32_bf16 v[64:67], v[160:163], v[192:195], v[64:67]
	s_setprio 0
	s_barrier
	s_nop 1
	s_add_i32 s3, s3, s33
	v_lshl_add_u64 v[196:197], s[28:29], 0, v[210:211]
	s_mov_b32 m0, s3
	ds_read_b128 v[164:167], v241 offset:16384
	ds_read_b128 v[168:171], v241 offset:17408
	ds_read_b128 v[172:175], v241 offset:18432
	ds_read_b128 v[176:179], v241 offset:19456
	ds_read_b128 v[180:183], v241 offset:20480
	ds_read_b128 v[184:187], v241 offset:21504
	ds_read_b128 v[188:191], v241 offset:22528
	ds_read_b128 v[192:195], v241 offset:23552
	global_load_lds_dwordx4 v[196:197], off
	s_add_i32 m0, s3, 0x2000
	s_add_u32 vcc_lo, s28, 0x160000
	v_lshl_add_u64 v[198:199], s[28:29], 0, v[220:221]
	s_addc_u32 vcc_hi, s29, 0
	s_add_i32 s3, s55, s33
	global_load_lds_dwordx4 v[198:199], off
	v_lshl_add_u64 v[200:201], vcc, 0, v[210:211]
	s_mov_b32 m0, s3
	v_lshl_add_u64 v[202:203], s[30:31], 0, v[218:219]
	global_load_lds_dwordx4 v[200:201], off
	v_lshl_add_u64 v[200:201], vcc, 0, v[220:221]
	s_add_i32 m0, s3, 0x2000
	s_nop 0
	global_load_lds_dwordx4 v[200:201], off
	v_lshl_add_u64 v[200:201], s[30:31], 0, v[208:209]
	s_mov_b32 m0, s11
	s_nop 0
	global_load_lds_dwordx4 v[200:201], off
	s_mov_b32 m0, s65
	s_nop 0
	global_load_lds_dwordx4 v[202:203], off
	s_waitcnt vmcnt(8)
	s_waitcnt lgkmcnt(0)
	s_barrier
	s_setprio 1
	s_waitcnt lgkmcnt(0)
	v_mfma_f32_16x16x32_bf16 v[60:63], v[76:79], v[164:167], 0
	v_mfma_f32_16x16x32_bf16 v[60:63], v[88:91], v[168:171], v[60:63]
	v_mfma_f32_16x16x32_bf16 v[52:55], v[76:79], v[172:175], 0
	v_mfma_f32_16x16x32_bf16 v[52:55], v[88:91], v[176:179], v[52:55]
	v_mfma_f32_16x16x32_bf16 v[44:47], v[76:79], v[180:183], 0
	v_mfma_f32_16x16x32_bf16 v[44:47], v[88:91], v[184:187], v[44:47]
	v_mfma_f32_16x16x32_bf16 v[36:39], v[76:79], v[188:191], 0
	v_mfma_f32_16x16x32_bf16 v[36:39], v[88:91], v[192:195], v[36:39]
	v_mfma_f32_16x16x32_bf16 v[56:59], v[100:103], v[164:167], 0
	v_mfma_f32_16x16x32_bf16 v[56:59], v[112:115], v[168:171], v[56:59]
	v_mfma_f32_16x16x32_bf16 v[48:51], v[100:103], v[172:175], 0
	v_mfma_f32_16x16x32_bf16 v[48:51], v[112:115], v[176:179], v[48:51]
	v_mfma_f32_16x16x32_bf16 v[40:43], v[100:103], v[180:183], 0
	v_mfma_f32_16x16x32_bf16 v[40:43], v[112:115], v[184:187], v[40:43]
	v_mfma_f32_16x16x32_bf16 v[32:35], v[100:103], v[188:191], 0
	v_mfma_f32_16x16x32_bf16 v[32:35], v[112:115], v[192:195], v[32:35]
	s_setprio 0
	s_setprio 1
	v_mfma_f32_16x16x32_bf16 v[28:31], v[124:127], v[164:167], 0
	v_mfma_f32_16x16x32_bf16 v[28:31], v[136:139], v[168:171], v[28:31]
	v_mfma_f32_16x16x32_bf16 v[20:23], v[124:127], v[172:175], 0
	v_mfma_f32_16x16x32_bf16 v[20:23], v[136:139], v[176:179], v[20:23]
	v_mfma_f32_16x16x32_bf16 v[12:15], v[124:127], v[180:183], 0
	v_mfma_f32_16x16x32_bf16 v[12:15], v[136:139], v[184:187], v[12:15]
	v_mfma_f32_16x16x32_bf16 v[4:7], v[124:127], v[188:191], 0
	v_mfma_f32_16x16x32_bf16 v[4:7], v[136:139], v[192:195], v[4:7]
	v_mfma_f32_16x16x32_bf16 v[24:27], v[148:151], v[164:167], 0
	v_mfma_f32_16x16x32_bf16 v[24:27], v[160:163], v[168:171], v[24:27]
	v_mfma_f32_16x16x32_bf16 v[16:19], v[148:151], v[172:175], 0
	v_mfma_f32_16x16x32_bf16 v[16:19], v[160:163], v[176:179], v[16:19]
	v_mfma_f32_16x16x32_bf16 v[8:11], v[148:151], v[180:183], 0
	v_mfma_f32_16x16x32_bf16 v[8:11], v[160:163], v[184:187], v[8:11]
	v_mfma_f32_16x16x32_bf16 v[0:3], v[148:151], v[188:191], 0
	v_mfma_f32_16x16x32_bf16 v[0:3], v[160:163], v[192:195], v[0:3]
	s_setprio 0
	s_barrier
	s_nop 1
	s_add_i32 s3, 0, 0x18000
	s_add_i32 s55, 0, 0x1c000
	v_add_u32_e32 v112, s3, v238
	v_add_u32_e32 v160, s55, v238
	ds_read_b128 v[76:79], v112
	ds_read_b128 v[88:91], v112 offset:1024
	ds_read_b128 v[100:103], v112 offset:2048
	ds_read_b128 v[112:115], v112 offset:3072
	ds_read_b128 v[124:127], v160
	ds_read_b128 v[136:139], v160 offset:1024
	ds_read_b128 v[148:151], v160 offset:2048
	ds_read_b128 v[160:163], v160 offset:3072
	s_add_u32 s30, s30, 0x160000
	s_addc_u32 s31, s31, 0
	s_mov_b32 m0, s34
	v_lshl_add_u64 v[204:205], s[30:31], 0, v[208:209]
	ds_read_b128 v[164:167], v241 offset:32768
	ds_read_b128 v[168:171], v241 offset:33792
	ds_read_b128 v[172:175], v241 offset:34816
	ds_read_b128 v[176:179], v241 offset:35840
	ds_read_b128 v[180:183], v241 offset:36864
	ds_read_b128 v[184:187], v241 offset:37888
	ds_read_b128 v[188:191], v241 offset:38912
	ds_read_b128 v[192:195], v241 offset:39936
	global_load_lds_dwordx4 v[204:205], off
	v_lshl_add_u64 v[204:205], s[30:31], 0, v[218:219]
	s_mov_b32 m0, s67
	s_nop 0
	global_load_lds_dwordx4 v[204:205], off
	s_waitcnt vmcnt(8)
	s_waitcnt lgkmcnt(0)
	s_barrier
	s_setprio 1
	s_waitcnt lgkmcnt(0)
	v_mfma_f32_16x16x32_bf16 v[156:159], v[76:79], v[164:167], v[156:159]
	v_mfma_f32_16x16x32_bf16 v[156:159], v[88:91], v[168:171], v[156:159]
	v_mfma_f32_16x16x32_bf16 v[144:147], v[76:79], v[172:175], v[144:147]
	v_mfma_f32_16x16x32_bf16 v[144:147], v[88:91], v[176:179], v[144:147]
	v_mfma_f32_16x16x32_bf16 v[132:135], v[76:79], v[180:183], v[132:135]
	v_mfma_f32_16x16x32_bf16 v[132:135], v[88:91], v[184:187], v[132:135]
	v_mfma_f32_16x16x32_bf16 v[120:123], v[76:79], v[188:191], v[120:123]
	v_mfma_f32_16x16x32_bf16 v[120:123], v[88:91], v[192:195], v[120:123]
	v_mfma_f32_16x16x32_bf16 v[152:155], v[100:103], v[164:167], v[152:155]
	v_mfma_f32_16x16x32_bf16 v[152:155], v[112:115], v[168:171], v[152:155]
	v_mfma_f32_16x16x32_bf16 v[140:143], v[100:103], v[172:175], v[140:143]
	v_mfma_f32_16x16x32_bf16 v[140:143], v[112:115], v[176:179], v[140:143]
	v_mfma_f32_16x16x32_bf16 v[128:131], v[100:103], v[180:183], v[128:131]
	v_mfma_f32_16x16x32_bf16 v[128:131], v[112:115], v[184:187], v[128:131]
	v_mfma_f32_16x16x32_bf16 v[116:119], v[100:103], v[188:191], v[116:119]
	v_mfma_f32_16x16x32_bf16 v[116:119], v[112:115], v[192:195], v[116:119]
	s_setprio 0
	s_setprio 1
	v_mfma_f32_16x16x32_bf16 v[108:111], v[124:127], v[164:167], v[108:111]
	v_mfma_f32_16x16x32_bf16 v[108:111], v[136:139], v[168:171], v[108:111]
	v_mfma_f32_16x16x32_bf16 v[96:99], v[124:127], v[172:175], v[96:99]
	v_mfma_f32_16x16x32_bf16 v[96:99], v[136:139], v[176:179], v[96:99]
	v_mfma_f32_16x16x32_bf16 v[84:87], v[124:127], v[180:183], v[84:87]
	v_mfma_f32_16x16x32_bf16 v[84:87], v[136:139], v[184:187], v[84:87]
	v_mfma_f32_16x16x32_bf16 v[72:75], v[124:127], v[188:191], v[72:75]
	v_mfma_f32_16x16x32_bf16 v[72:75], v[136:139], v[192:195], v[72:75]
	v_mfma_f32_16x16x32_bf16 v[104:107], v[148:151], v[164:167], v[104:107]
	v_mfma_f32_16x16x32_bf16 v[104:107], v[160:163], v[168:171], v[104:107]
	v_mfma_f32_16x16x32_bf16 v[92:95], v[148:151], v[172:175], v[92:95]
	v_mfma_f32_16x16x32_bf16 v[92:95], v[160:163], v[176:179], v[92:95]
	v_mfma_f32_16x16x32_bf16 v[80:83], v[148:151], v[180:183], v[80:83]
	v_mfma_f32_16x16x32_bf16 v[80:83], v[160:163], v[184:187], v[80:83]
	v_mfma_f32_16x16x32_bf16 v[64:67], v[148:151], v[188:191], v[64:67]
	v_mfma_f32_16x16x32_bf16 v[64:67], v[160:163], v[192:195], v[64:67]
	s_setprio 0
	s_barrier
	s_nop 1
	s_add_i32 s3, s3, s33
	v_lshl_add_u64 v[196:197], v[196:197], 0, s[72:73]
	s_mov_b32 m0, s3
	ds_read_b128 v[164:167], v241 offset:49152
	ds_read_b128 v[168:171], v241 offset:50176
	ds_read_b128 v[172:175], v241 offset:51200
	ds_read_b128 v[176:179], v241 offset:52224
	ds_read_b128 v[180:183], v241 offset:53248
	ds_read_b128 v[184:187], v241 offset:54272
	ds_read_b128 v[188:191], v241 offset:55296
	ds_read_b128 v[192:195], v241 offset:56320
	global_load_lds_dwordx4 v[196:197], off
	s_add_i32 m0, s3, 0x2000
	s_add_u32 s28, s28, 0x160080
	v_lshl_add_u64 v[196:197], v[198:199], 0, s[72:73]
	s_addc_u32 s29, s29, 0
	s_add_i32 s3, s55, s33
	global_load_lds_dwordx4 v[196:197], off
	v_lshl_add_u64 v[196:197], s[28:29], 0, v[210:211]
	s_mov_b32 m0, s3
	s_nop 0
	global_load_lds_dwordx4 v[196:197], off
	v_lshl_add_u64 v[196:197], s[28:29], 0, v[220:221]
	s_add_i32 m0, s3, 0x2000
	s_nop 0
	global_load_lds_dwordx4 v[196:197], off
	v_lshl_add_u64 v[196:197], v[200:201], 0, s[72:73]
	s_mov_b32 m0, s81
	s_nop 0
	global_load_lds_dwordx4 v[196:197], off
	v_lshl_add_u64 v[196:197], v[202:203], 0, s[72:73]
	s_mov_b32 m0, s82
	s_nop 0
	global_load_lds_dwordx4 v[196:197], off
	s_waitcnt vmcnt(8)
	s_waitcnt lgkmcnt(0)
	s_barrier
	s_setprio 1
	s_waitcnt lgkmcnt(0)
	v_mfma_f32_16x16x32_bf16 v[60:63], v[76:79], v[164:167], v[60:63]
	v_mfma_f32_16x16x32_bf16 v[60:63], v[88:91], v[168:171], v[60:63]
	v_mfma_f32_16x16x32_bf16 v[52:55], v[76:79], v[172:175], v[52:55]
	v_mfma_f32_16x16x32_bf16 v[52:55], v[88:91], v[176:179], v[52:55]
	v_mfma_f32_16x16x32_bf16 v[44:47], v[76:79], v[180:183], v[44:47]
	v_mfma_f32_16x16x32_bf16 v[44:47], v[88:91], v[184:187], v[44:47]
	v_mfma_f32_16x16x32_bf16 v[36:39], v[76:79], v[188:191], v[36:39]
	v_mfma_f32_16x16x32_bf16 v[36:39], v[88:91], v[192:195], v[36:39]
	v_mfma_f32_16x16x32_bf16 v[56:59], v[100:103], v[164:167], v[56:59]
	v_mfma_f32_16x16x32_bf16 v[56:59], v[112:115], v[168:171], v[56:59]
	v_mfma_f32_16x16x32_bf16 v[48:51], v[100:103], v[172:175], v[48:51]
	v_mfma_f32_16x16x32_bf16 v[48:51], v[112:115], v[176:179], v[48:51]
	v_mfma_f32_16x16x32_bf16 v[40:43], v[100:103], v[180:183], v[40:43]
	v_mfma_f32_16x16x32_bf16 v[40:43], v[112:115], v[184:187], v[40:43]
	v_mfma_f32_16x16x32_bf16 v[32:35], v[100:103], v[188:191], v[32:35]
	v_mfma_f32_16x16x32_bf16 v[32:35], v[112:115], v[192:195], v[32:35]
	s_setprio 0
	s_setprio 1
	v_mfma_f32_16x16x32_bf16 v[28:31], v[124:127], v[164:167], v[28:31]
	v_mfma_f32_16x16x32_bf16 v[28:31], v[136:139], v[168:171], v[28:31]
	v_mfma_f32_16x16x32_bf16 v[20:23], v[124:127], v[172:175], v[20:23]
	v_mfma_f32_16x16x32_bf16 v[20:23], v[136:139], v[176:179], v[20:23]
	v_mfma_f32_16x16x32_bf16 v[12:15], v[124:127], v[180:183], v[12:15]
	v_mfma_f32_16x16x32_bf16 v[12:15], v[136:139], v[184:187], v[12:15]
	v_mfma_f32_16x16x32_bf16 v[4:7], v[124:127], v[188:191], v[4:7]
	v_mfma_f32_16x16x32_bf16 v[4:7], v[136:139], v[192:195], v[4:7]
	v_mfma_f32_16x16x32_bf16 v[24:27], v[148:151], v[164:167], v[24:27]
	v_mfma_f32_16x16x32_bf16 v[24:27], v[160:163], v[168:171], v[24:27]
	v_mfma_f32_16x16x32_bf16 v[16:19], v[148:151], v[172:175], v[16:19]
	v_mfma_f32_16x16x32_bf16 v[16:19], v[160:163], v[176:179], v[16:19]
	v_mfma_f32_16x16x32_bf16 v[8:11], v[148:151], v[180:183], v[8:11]
	v_mfma_f32_16x16x32_bf16 v[8:11], v[160:163], v[184:187], v[8:11]
	v_mfma_f32_16x16x32_bf16 v[0:3], v[148:151], v[188:191], v[0:3]
	v_mfma_f32_16x16x32_bf16 v[0:3], v[160:163], v[192:195], v[0:3]
	s_setprio 0
	s_barrier
	s_nop 1
	s_add_u32 s26, s26, 0x100
	s_addc_u32 s27, s27, 0
	s_cmp_ge_i32 s2, s17
	s_mov_b32 s28, s2
	s_cbranch_scc1 .LBB0_1669
	s_branch .LBB0_1661
